# v7 + EpiUpF (fused up-projection) epilogue rewritten: swapped MFMA operands, row-contiguous 2-byte gate loads and bf16 stores, batched with counted waits
# speedup vs baseline: 1.0097x; 1.0097x over previous
; #define PG8_STAGE(bufoff, gbase, voff) do { _Pragma("unroll") for (int _i = 0; _i < 2; ++_i) \
;         __builtin_amdgcn_global_load_lds((const unsigned*)((const char*)(gbase) + (voff)[_i]), (PG8_LAS unsigned*)(lds + (bufoff) + ldsw + _i * 8192), 16, 0, 0); } while (0)
; #define PG8_LDA(dst, b, h) do { _Pragma("unroll") for (int m = 0; m < 4; ++m) _Pragma("unroll") for (int k = 0; k < 2; ++k) dst[m][k] = *(const PG8_LAS bf16x8*)(lds + PG8_SA(b, h) + aoff + m * 2048 + k * 1024); } while (0)
; #define PG8_LDB(dst, b, h) do { _Pragma("unroll") for (int n = 0; n < 2; ++n) _Pragma("unroll") for (int k = 0; k < 2; ++k) dst[n][k] = *(const PG8_LAS bf16x8*)(lds + PG8_SB(b, h) + boff + n * 2048 + k * 1024); } while (0)
; #define PG8_MMA(ai, bj, At, Bt) do { __builtin_amdgcn_s_setprio(1); _Pragma("unroll") for (int m = 0; m < 4; ++m) _Pragma("unroll") for (int n = 0; n < 2; ++n) _Pragma("unroll") for (int k = 0; k < 2; ++k) \
;         acc[ai][bj][m][n] = __builtin_amdgcn_mfma_f32_16x16x32_bf16(Bt[n][k], At[m][k], acc[ai][bj][m][n], 0, 0, 0); __builtin_amdgcn_s_setprio(0); } while (0)
; template <class Epi, class Sched, bool ALIGN_EPI = false, bool SP2 = false>
; __device__ __forceinline__ void gemm_phase(PG8_LAS unsigned char* lds, const Gemm g, const Sched& S, const Epi& E, int wave_s) {
;     ...
;         for (int t = 0; t < nt; t += 2) {
;             const bool last = (t == nt - 2);
;             const char* a1 = cA + (size_t)(t + 1) * kstep;
;             const char* a2 = last ? nA : cA + (size_t)(t + 2) * kstep; const char* b2 = last ? nB : cB + (size_t)(t + 2) * kstep;
;             const char* a3 = a2 + kstep; const char* b3 = b2 + kstep;
;             if (last && has_next) S.a_ready(nxt);
;             if constexpr (Epi::HAS_MID) { if (t == nt / 2) E.mid(acc, cur, wr, wc, fr, fq); }
;             if constexpr (SP2) {
;             PG8_LDB(B0, 0, 0); PG8_LDB(B1, 0, 1); PG8_SCHED; PG8_LDA(At, 0, 0); PG8_STAGE(PG8_SA(1, 1), a1 + hstepA, voffA);
;             PG8_WAIT_V(8); PG8_WAIT_L(0); PG8_BAR; PG8_MMA(0, 0, At, B0); PG8_MMA(0, 1, At, B1); PG8_BAR; PG8_SCHED;
;             PG8_LDA(At, 0, 1); PG8_STAGE(PG8_SB(0, 0), b2, voffB); PG8_STAGE(PG8_SB(0, 1), b2 + hstepB, voffB); PG8_STAGE(PG8_SA(0, 0), a2, voffA);
;             PG8_WAIT_V(8); PG8_WAIT_L(0); PG8_BAR; PG8_MMA(1, 0, At, B0); PG8_MMA(1, 1, At, B1); PG8_BAR; PG8_SCHED;
.LBB0_1601:
	s_add_u32 s0, s56, s64
	s_addc_u32 s1, s57, s65
	s_add_u32 s0, s0, 0x100
	s_addc_u32 s1, s1, 0
	s_add_u32 s26, s48, s64
	s_addc_u32 s27, s49, s65
	s_cmpk_eq_i32 s64, 0xf00
	s_cselect_b32 s7, s36, s1
	s_cselect_b32 s6, s37, s0
	s_cselect_b32 s1, s25, s27
	s_cselect_b32 s0, s47, s26
	s_add_i32 s26, 0, 0x10000
	v_add_u32_e32 v0, s26, v155
	s_add_i32 s33, 0, 0x14000
	ds_read_b128 v[148:151], v0
	ds_read_b128 v[158:161], v0 offset:1024
	ds_read_b128 v[162:165], v0 offset:2048
	ds_read_b128 v[166:169], v0 offset:3072
	v_add_u32_e32 v0, s33, v155
	ds_read_b128 v[176:179], v0
	ds_read_b128 v[180:183], v0 offset:1024
	ds_read_b128 v[184:187], v0 offset:2048
	ds_read_b128 v[188:191], v0 offset:3072
	v_lshl_add_u64 v[2:3], v[146:147], 0, s[64:65]
	s_add_i32 m0, s16, 0xc000
	ds_read_b128 v[192:195], v157
	ds_read_b128 v[196:199], v157 offset:1024
	ds_read_b128 v[208:211], v157 offset:2048
	ds_read_b128 v[212:215], v157 offset:3072
	ds_read_b128 v[216:219], v157 offset:4096
	ds_read_b128 v[220:223], v157 offset:5120
	ds_read_b128 v[224:227], v157 offset:6144
	ds_read_b128 v[228:231], v157 offset:7168
	global_load_lds_dwordx4 v[2:3], off
	v_lshl_add_u64 v[2:3], v[144:145], 0, s[64:65]
	s_add_i32 m0, s16, 0xe000
	s_nop 0
	global_load_lds_dwordx4 v[2:3], off
	s_waitcnt vmcnt(8)
	s_waitcnt lgkmcnt(0)
	s_barrier
	s_setprio 1
	s_waitcnt lgkmcnt(0)
	v_mfma_f32_16x16x32_bf16 v[128:131], v[192:195], v[148:151], v[128:131]
	v_mfma_f32_16x16x32_bf16 v[124:127], v[192:195], v[162:165], v[124:127]
	v_mfma_f32_16x16x32_bf16 v[112:115], v[208:211], v[148:151], v[112:115]
	v_mfma_f32_16x16x32_bf16 v[108:111], v[208:211], v[162:165], v[108:111]
	v_mfma_f32_16x16x32_bf16 v[96:99], v[216:219], v[148:151], v[96:99]
	v_mfma_f32_16x16x32_bf16 v[92:95], v[216:219], v[162:165], v[92:95]
	v_mfma_f32_16x16x32_bf16 v[80:83], v[224:227], v[148:151], v[80:83]
	v_mfma_f32_16x16x32_bf16 v[76:79], v[224:227], v[162:165], v[76:79]
	v_mfma_f32_16x16x32_bf16 v[128:131], v[196:199], v[158:161], v[128:131]
	v_mfma_f32_16x16x32_bf16 v[124:127], v[196:199], v[166:169], v[124:127]
	v_mfma_f32_16x16x32_bf16 v[112:115], v[212:215], v[158:161], v[112:115]
	v_mfma_f32_16x16x32_bf16 v[108:111], v[212:215], v[166:169], v[108:111]
	v_mfma_f32_16x16x32_bf16 v[96:99], v[220:223], v[158:161], v[96:99]
	v_mfma_f32_16x16x32_bf16 v[92:95], v[220:223], v[166:169], v[92:95]
	v_mfma_f32_16x16x32_bf16 v[80:83], v[228:231], v[158:161], v[80:83]
	v_mfma_f32_16x16x32_bf16 v[76:79], v[228:231], v[166:169], v[76:79]
	s_setprio 0
	s_setprio 1
	v_mfma_f32_16x16x32_bf16 v[120:123], v[192:195], v[176:179], v[120:123]
	v_mfma_f32_16x16x32_bf16 v[116:119], v[192:195], v[184:187], v[116:119]
	v_mfma_f32_16x16x32_bf16 v[104:107], v[208:211], v[176:179], v[104:107]
	v_mfma_f32_16x16x32_bf16 v[100:103], v[208:211], v[184:187], v[100:103]
	v_mfma_f32_16x16x32_bf16 v[88:91], v[216:219], v[176:179], v[88:91]
	v_mfma_f32_16x16x32_bf16 v[84:87], v[216:219], v[184:187], v[84:87]
	v_mfma_f32_16x16x32_bf16 v[72:75], v[224:227], v[176:179], v[72:75]
	v_mfma_f32_16x16x32_bf16 v[68:71], v[224:227], v[184:187], v[68:71]
	v_mfma_f32_16x16x32_bf16 v[120:123], v[196:199], v[180:183], v[120:123]
	v_mfma_f32_16x16x32_bf16 v[116:119], v[196:199], v[188:191], v[116:119]
	v_mfma_f32_16x16x32_bf16 v[104:107], v[212:215], v[180:183], v[104:107]
	v_mfma_f32_16x16x32_bf16 v[100:103], v[212:215], v[188:191], v[100:103]
	v_mfma_f32_16x16x32_bf16 v[88:91], v[220:223], v[180:183], v[88:91]
	v_mfma_f32_16x16x32_bf16 v[84:87], v[220:223], v[188:191], v[84:87]
	v_mfma_f32_16x16x32_bf16 v[72:75], v[228:231], v[180:183], v[72:75]
	v_mfma_f32_16x16x32_bf16 v[68:71], v[228:231], v[188:191], v[68:71]
	s_setprio 0
	s_barrier
	s_add_i32 s26, s26, s13
	v_lshl_add_u64 v[152:153], s[0:1], 0, v[134:135]
	s_mov_b32 m0, s26
	ds_read_b128 v[192:195], v157 offset:16384
	ds_read_b128 v[196:199], v157 offset:17408
	ds_read_b128 v[208:211], v157 offset:18432
	ds_read_b128 v[212:215], v157 offset:19456
	ds_read_b128 v[216:219], v157 offset:20480
	ds_read_b128 v[220:223], v157 offset:21504
	ds_read_b128 v[224:227], v157 offset:22528
	ds_read_b128 v[228:231], v157 offset:23552
	global_load_lds_dwordx4 v[152:153], off
	s_add_i32 m0, s26, 0x2000
	s_add_u32 s26, s0, 0x80000
	v_lshl_add_u64 v[170:171], s[0:1], 0, v[132:133]
	s_addc_u32 s27, s1, 0
	s_add_i32 s33, s33, s13
	global_load_lds_dwordx4 v[170:171], off
	v_lshl_add_u64 v[2:3], s[26:27], 0, v[134:135]
	s_mov_b32 m0, s33
	v_lshl_add_u64 v[200:201], s[6:7], 0, v[134:135]
	global_load_lds_dwordx4 v[2:3], off
	v_lshl_add_u64 v[2:3], s[26:27], 0, v[132:133]
	s_add_i32 m0, s33, 0x2000
	v_lshl_add_u64 v[232:233], s[6:7], 0, v[132:133]
	global_load_lds_dwordx4 v[2:3], off
	s_mov_b32 m0, s16
	s_nop 0
	global_load_lds_dwordx4 v[200:201], off
	s_mov_b32 m0, s17
	s_nop 0
	global_load_lds_dwordx4 v[232:233], off
	s_waitcnt vmcnt(8)
	s_waitcnt lgkmcnt(0)
	s_barrier
; #define PG8_STAGE(bufoff, gbase, voff) do { _Pragma("unroll") for (int _i = 0; _i < 2; ++_i) \
;         __builtin_amdgcn_global_load_lds((const unsigned*)((const char*)(gbase) + (voff)[_i]), (PG8_LAS unsigned*)(lds + (bufoff) + ldsw + _i * 8192), 16, 0, 0); } while (0)
; #define PG8_LDA(dst, b, h) do { _Pragma("unroll") for (int m = 0; m < 4; ++m) _Pragma("unroll") for (int k = 0; k < 2; ++k) dst[m][k] = *(const PG8_LAS bf16x8*)(lds + PG8_SA(b, h) + aoff + m * 2048 + k * 1024); } while (0)
; #define PG8_LDB(dst, b, h) do { _Pragma("unroll") for (int n = 0; n < 2; ++n) _Pragma("unroll") for (int k = 0; k < 2; ++k) dst[n][k] = *(const PG8_LAS bf16x8*)(lds + PG8_SB(b, h) + boff + n * 2048 + k * 1024); } while (0)
; #define PG8_MMA(ai, bj, At, Bt) do { __builtin_amdgcn_s_setprio(1); _Pragma("unroll") for (int m = 0; m < 4; ++m) _Pragma("unroll") for (int n = 0; n < 2; ++n) _Pragma("unroll") for (int k = 0; k < 2; ++k) \
;         acc[ai][bj][m][n] = __builtin_amdgcn_mfma_f32_16x16x32_bf16(Bt[n][k], At[m][k], acc[ai][bj][m][n], 0, 0, 0); __builtin_amdgcn_s_setprio(0); } while (0)
; #define PG8_WAIT_V(n) asm volatile("s_waitcnt vmcnt(" #n ")" ::: "memory")
; #define PG8_WAIT_L(n) asm volatile("s_waitcnt lgkmcnt(" #n ")" ::: "memory")
; #define PG8_BAR __builtin_amdgcn_s_barrier()
; #define PG8_SCHED __builtin_amdgcn_sched_barrier(0)
; template <class Epi, class Sched, bool ALIGN_EPI = false, bool SP2 = false>
; __device__ __forceinline__ void gemm_phase(PG8_LAS unsigned char* lds, const Gemm g, const Sched& S, const Epi& E, int wave_s) {
;     ...
;             PG8_WAIT_V(8); PG8_WAIT_L(0); PG8_BAR; PG8_MMA(1, 0, At, B0); PG8_MMA(1, 1, At, B1); PG8_BAR; PG8_SCHED;
;             PG8_LDB(B0, 1, 0); PG8_LDB(B1, 1, 1); PG8_SCHED; PG8_LDA(At, 1, 0); PG8_STAGE(PG8_SA(0, 1), a2 + hstepA, voffA);
;             PG8_WAIT_V(8); PG8_WAIT_L(0); PG8_BAR; PG8_MMA(0, 0, At, B0); PG8_MMA(0, 1, At, B1); PG8_BAR; PG8_SCHED;
	s_setprio 1
	s_waitcnt lgkmcnt(0)
	v_mfma_f32_16x16x32_bf16 v[64:67], v[192:195], v[148:151], v[64:67]
	v_mfma_f32_16x16x32_bf16 v[60:63], v[192:195], v[162:165], v[60:63]
	v_mfma_f32_16x16x32_bf16 v[48:51], v[208:211], v[148:151], v[48:51]
	v_mfma_f32_16x16x32_bf16 v[44:47], v[208:211], v[162:165], v[44:47]
	v_mfma_f32_16x16x32_bf16 v[32:35], v[216:219], v[148:151], v[32:35]
	v_mfma_f32_16x16x32_bf16 v[28:31], v[216:219], v[162:165], v[28:31]
	v_mfma_f32_16x16x32_bf16 v[16:19], v[224:227], v[148:151], v[16:19]
	v_mfma_f32_16x16x32_bf16 v[12:15], v[224:227], v[162:165], v[12:15]
	v_mfma_f32_16x16x32_bf16 v[64:67], v[196:199], v[158:161], v[64:67]
	v_mfma_f32_16x16x32_bf16 v[60:63], v[196:199], v[166:169], v[60:63]
	v_mfma_f32_16x16x32_bf16 v[48:51], v[212:215], v[158:161], v[48:51]
	v_mfma_f32_16x16x32_bf16 v[44:47], v[212:215], v[166:169], v[44:47]
	v_mfma_f32_16x16x32_bf16 v[32:35], v[220:223], v[158:161], v[32:35]
	v_mfma_f32_16x16x32_bf16 v[28:31], v[220:223], v[166:169], v[28:31]
	v_mfma_f32_16x16x32_bf16 v[16:19], v[228:231], v[158:161], v[16:19]
	v_mfma_f32_16x16x32_bf16 v[12:15], v[228:231], v[166:169], v[12:15]
	s_setprio 0
	s_setprio 1
	v_mfma_f32_16x16x32_bf16 v[56:59], v[192:195], v[176:179], v[56:59]
	v_mfma_f32_16x16x32_bf16 v[52:55], v[192:195], v[184:187], v[52:55]
	v_mfma_f32_16x16x32_bf16 v[40:43], v[208:211], v[176:179], v[40:43]
	v_mfma_f32_16x16x32_bf16 v[36:39], v[208:211], v[184:187], v[36:39]
	v_mfma_f32_16x16x32_bf16 v[24:27], v[216:219], v[176:179], v[24:27]
	v_mfma_f32_16x16x32_bf16 v[20:23], v[216:219], v[184:187], v[20:23]
	v_mfma_f32_16x16x32_bf16 v[8:11], v[224:227], v[176:179], v[8:11]
	v_mfma_f32_16x16x32_bf16 v[2:5], v[224:227], v[184:187], v[4:7]
	v_mfma_f32_16x16x32_bf16 v[56:59], v[196:199], v[180:183], v[56:59]
	v_mfma_f32_16x16x32_bf16 v[52:55], v[196:199], v[188:191], v[52:55]
	v_mfma_f32_16x16x32_bf16 v[40:43], v[212:215], v[180:183], v[40:43]
	v_mfma_f32_16x16x32_bf16 v[36:39], v[212:215], v[188:191], v[36:39]
	v_mfma_f32_16x16x32_bf16 v[24:27], v[220:223], v[180:183], v[24:27]
	v_mfma_f32_16x16x32_bf16 v[20:23], v[220:223], v[188:191], v[20:23]
	v_mfma_f32_16x16x32_bf16 v[8:11], v[228:231], v[180:183], v[8:11]
	v_mfma_f32_16x16x32_bf16 v[2:5], v[228:231], v[188:191], v[2:5]
	s_setprio 0
	s_barrier
	s_add_i32 s26, 0, 0x18000
	v_add_u32_e32 v0, s26, v155
	s_add_i32 s27, 0, 0x1c000
	ds_read_b128 v[148:151], v0
	ds_read_b128 v[158:161], v0 offset:1024
	ds_read_b128 v[162:165], v0 offset:2048
	ds_read_b128 v[166:169], v0 offset:3072
	v_add_u32_e32 v0, s27, v155
	ds_read_b128 v[176:179], v0
	ds_read_b128 v[180:183], v0 offset:1024
	ds_read_b128 v[184:187], v0 offset:2048
	ds_read_b128 v[188:191], v0 offset:3072
	s_add_u32 s6, s6, 0x80000
	s_addc_u32 s7, s7, 0
	s_mov_b32 m0, s18
	v_lshl_add_u64 v[6:7], s[6:7], 0, v[134:135]
	ds_read_b128 v[192:195], v157 offset:32768
	ds_read_b128 v[196:199], v157 offset:33792
	ds_read_b128 v[208:211], v157 offset:34816
	ds_read_b128 v[212:215], v157 offset:35840
	ds_read_b128 v[216:219], v157 offset:36864
	ds_read_b128 v[220:223], v157 offset:37888
	ds_read_b128 v[224:227], v157 offset:38912
	ds_read_b128 v[228:231], v157 offset:39936
	global_load_lds_dwordx4 v[6:7], off
	v_lshl_add_u64 v[6:7], s[6:7], 0, v[132:133]
	s_mov_b32 m0, s19
	s_nop 0
	global_load_lds_dwordx4 v[6:7], off
	s_waitcnt vmcnt(8)
	s_waitcnt lgkmcnt(0)
	s_barrier
	s_setprio 1
	s_waitcnt lgkmcnt(0)
	v_mfma_f32_16x16x32_bf16 v[128:131], v[192:195], v[148:151], v[128:131]
	v_mfma_f32_16x16x32_bf16 v[124:127], v[192:195], v[162:165], v[124:127]
	v_mfma_f32_16x16x32_bf16 v[112:115], v[208:211], v[148:151], v[112:115]
	v_mfma_f32_16x16x32_bf16 v[108:111], v[208:211], v[162:165], v[108:111]
	v_mfma_f32_16x16x32_bf16 v[96:99], v[216:219], v[148:151], v[96:99]
	v_mfma_f32_16x16x32_bf16 v[92:95], v[216:219], v[162:165], v[92:95]
	v_mfma_f32_16x16x32_bf16 v[80:83], v[224:227], v[148:151], v[80:83]
	v_mfma_f32_16x16x32_bf16 v[76:79], v[224:227], v[162:165], v[76:79]
	v_mfma_f32_16x16x32_bf16 v[128:131], v[196:199], v[158:161], v[128:131]
	v_mfma_f32_16x16x32_bf16 v[124:127], v[196:199], v[166:169], v[124:127]
	v_mfma_f32_16x16x32_bf16 v[112:115], v[212:215], v[158:161], v[112:115]
	v_mfma_f32_16x16x32_bf16 v[108:111], v[212:215], v[166:169], v[108:111]
	v_mfma_f32_16x16x32_bf16 v[96:99], v[220:223], v[158:161], v[96:99]
	v_mfma_f32_16x16x32_bf16 v[92:95], v[220:223], v[166:169], v[92:95]
	v_mfma_f32_16x16x32_bf16 v[80:83], v[228:231], v[158:161], v[80:83]
	v_mfma_f32_16x16x32_bf16 v[76:79], v[228:231], v[166:169], v[76:79]
	s_setprio 0
	s_setprio 1
	v_mfma_f32_16x16x32_bf16 v[120:123], v[192:195], v[176:179], v[120:123]
	v_mfma_f32_16x16x32_bf16 v[116:119], v[192:195], v[184:187], v[116:119]
	v_mfma_f32_16x16x32_bf16 v[104:107], v[208:211], v[176:179], v[104:107]
	v_mfma_f32_16x16x32_bf16 v[100:103], v[208:211], v[184:187], v[100:103]
	v_mfma_f32_16x16x32_bf16 v[88:91], v[216:219], v[176:179], v[88:91]
	v_mfma_f32_16x16x32_bf16 v[84:87], v[216:219], v[184:187], v[84:87]
	v_mfma_f32_16x16x32_bf16 v[72:75], v[224:227], v[176:179], v[72:75]
	v_mfma_f32_16x16x32_bf16 v[68:71], v[224:227], v[184:187], v[68:71]
	v_mfma_f32_16x16x32_bf16 v[120:123], v[196:199], v[180:183], v[120:123]
	v_mfma_f32_16x16x32_bf16 v[116:119], v[196:199], v[188:191], v[116:119]
	v_mfma_f32_16x16x32_bf16 v[104:107], v[212:215], v[180:183], v[104:107]
	v_mfma_f32_16x16x32_bf16 v[100:103], v[212:215], v[188:191], v[100:103]
	v_mfma_f32_16x16x32_bf16 v[88:91], v[220:223], v[180:183], v[88:91]
	v_mfma_f32_16x16x32_bf16 v[84:87], v[220:223], v[188:191], v[84:87]
	v_mfma_f32_16x16x32_bf16 v[72:75], v[228:231], v[180:183], v[72:75]
	v_mfma_f32_16x16x32_bf16 v[68:71], v[228:231], v[188:191], v[68:71]
	s_setprio 0
	s_barrier
; #define PG8_STAGE(bufoff, gbase, voff) do { _Pragma("unroll") for (int _i = 0; _i < 2; ++_i) \
;         __builtin_amdgcn_global_load_lds((const unsigned*)((const char*)(gbase) + (voff)[_i]), (PG8_LAS unsigned*)(lds + (bufoff) + ldsw + _i * 8192), 16, 0, 0); } while (0)
; #define PG8_LDA(dst, b, h) do { _Pragma("unroll") for (int m = 0; m < 4; ++m) _Pragma("unroll") for (int k = 0; k < 2; ++k) dst[m][k] = *(const PG8_LAS bf16x8*)(lds + PG8_SA(b, h) + aoff + m * 2048 + k * 1024); } while (0)
; #define PG8_MMA(ai, bj, At, Bt) do { __builtin_amdgcn_s_setprio(1); _Pragma("unroll") for (int m = 0; m < 4; ++m) _Pragma("unroll") for (int n = 0; n < 2; ++n) _Pragma("unroll") for (int k = 0; k < 2; ++k) \
;         acc[ai][bj][m][n] = __builtin_amdgcn_mfma_f32_16x16x32_bf16(Bt[n][k], At[m][k], acc[ai][bj][m][n], 0, 0, 0); __builtin_amdgcn_s_setprio(0); } while (0)
; #define PG8_WAIT_V(n) asm volatile("s_waitcnt vmcnt(" #n ")" ::: "memory")
; #define PG8_WAIT_L(n) asm volatile("s_waitcnt lgkmcnt(" #n ")" ::: "memory")
; template <class Epi, class Sched, bool ALIGN_EPI = false, bool SP2 = false>
; __device__ __forceinline__ void gemm_phase(PG8_LAS unsigned char* lds, const Gemm g, const Sched& S, const Epi& E, int wave_s) {
;     ...
;             PG8_WAIT_V(8); PG8_WAIT_L(0); PG8_BAR; PG8_MMA(0, 0, At, B0); PG8_MMA(0, 1, At, B1); PG8_BAR; PG8_SCHED;
;             PG8_LDA(At, 1, 1); PG8_STAGE(PG8_SB(1, 0), b3, voffB); PG8_STAGE(PG8_SB(1, 1), b3 + hstepB, voffB); PG8_STAGE(PG8_SA(1, 0), a3, voffA);
;             PG8_WAIT_V(8); PG8_WAIT_L(0); PG8_BAR; PG8_MMA(1, 0, At, B0); PG8_MMA(1, 1, At, B1); PG8_BAR; PG8_SCHED;
;     __device__ __forceinline__ void mid(pg8::f32x4 (&acc)[2][2][4][2], const pg8::Unit& u, int wr, int wc, int fr, int fq) const {
;         int row0 = u.pm * 256 + wr * 64 + fr, col0 = u.pn * 256 + wc * 32 + 4 * fq;
;         asm volatile("" : "+v"(row0), "+v"(col0));
; #pragma unroll
;         for (int ai = 0; ai < 2; ++ai)
; #pragma unroll
;             for (int m = 0; m < 4; ++m) { const bf16* ap = AM + (size_t)(row0 + ai * 128 + m * 16) * 4096 + col0;
; #pragma unroll
;                 for (int bj = 0; bj < 2; ++bj)
; #pragma unroll
;                     for (int n = 0; n < 2; ++n) { const int c = bj * 128 + n * 16;
;                         const pg8::f32x4 a0 = up4(*(const pg8::u32x2*)(ap + c)), a1 = up4(*(const pg8::u32x2*)(ap + 2048 + c));
	s_add_i32 s6, s26, s13
	v_lshl_add_u64 v[6:7], v[152:153], 0, s[30:31]
	s_mov_b32 m0, s6
	ds_read_b128 v[192:195], v157 offset:49152
	ds_read_b128 v[196:199], v157 offset:50176
	ds_read_b128 v[208:211], v157 offset:51200
	ds_read_b128 v[212:215], v157 offset:52224
	ds_read_b128 v[216:219], v157 offset:53248
	ds_read_b128 v[220:223], v157 offset:54272
	ds_read_b128 v[224:227], v157 offset:55296
	ds_read_b128 v[228:231], v157 offset:56320
	global_load_lds_dwordx4 v[6:7], off
	s_add_i32 m0, s6, 0x2000
	s_add_u32 s0, s0, 0x80080
	v_lshl_add_u64 v[6:7], v[170:171], 0, s[30:31]
	s_addc_u32 s1, s1, 0
	s_add_i32 s6, s27, s13
	global_load_lds_dwordx4 v[6:7], off
	v_lshl_add_u64 v[6:7], s[0:1], 0, v[134:135]
	s_mov_b32 m0, s6
	s_nop 0
	global_load_lds_dwordx4 v[6:7], off
	v_lshl_add_u64 v[6:7], s[0:1], 0, v[132:133]
	s_add_i32 m0, s6, 0x2000
	s_nop 0
	global_load_lds_dwordx4 v[6:7], off
	v_lshl_add_u64 v[6:7], v[200:201], 0, s[30:31]
	s_mov_b32 m0, s20
	s_nop 0
	global_load_lds_dwordx4 v[6:7], off
	v_lshl_add_u64 v[6:7], v[232:233], 0, s[30:31]
	s_mov_b32 m0, s21
	s_nop 0
	global_load_lds_dwordx4 v[6:7], off
	s_waitcnt vmcnt(8)
	s_waitcnt lgkmcnt(0)
	s_barrier
	s_setprio 1
	s_waitcnt lgkmcnt(0)
	v_mfma_f32_16x16x32_bf16 v[64:67], v[192:195], v[148:151], v[64:67]
	v_mfma_f32_16x16x32_bf16 v[60:63], v[192:195], v[162:165], v[60:63]
	v_mfma_f32_16x16x32_bf16 v[48:51], v[208:211], v[148:151], v[48:51]
	v_mfma_f32_16x16x32_bf16 v[44:47], v[208:211], v[162:165], v[44:47]
	v_mfma_f32_16x16x32_bf16 v[32:35], v[216:219], v[148:151], v[32:35]
	v_mfma_f32_16x16x32_bf16 v[28:31], v[216:219], v[162:165], v[28:31]
	v_mfma_f32_16x16x32_bf16 v[16:19], v[224:227], v[148:151], v[16:19]
	v_mfma_f32_16x16x32_bf16 v[12:15], v[224:227], v[162:165], v[12:15]
	v_mfma_f32_16x16x32_bf16 v[64:67], v[196:199], v[158:161], v[64:67]
	v_mfma_f32_16x16x32_bf16 v[60:63], v[196:199], v[166:169], v[60:63]
	v_mfma_f32_16x16x32_bf16 v[48:51], v[212:215], v[158:161], v[48:51]
	v_mfma_f32_16x16x32_bf16 v[44:47], v[212:215], v[166:169], v[44:47]
	v_mfma_f32_16x16x32_bf16 v[32:35], v[220:223], v[158:161], v[32:35]
	v_mfma_f32_16x16x32_bf16 v[28:31], v[220:223], v[166:169], v[28:31]
	v_mfma_f32_16x16x32_bf16 v[16:19], v[228:231], v[158:161], v[16:19]
	v_mfma_f32_16x16x32_bf16 v[12:15], v[228:231], v[166:169], v[12:15]
	s_setprio 0
	s_setprio 1
	v_mfma_f32_16x16x32_bf16 v[56:59], v[192:195], v[176:179], v[56:59]
	v_mfma_f32_16x16x32_bf16 v[52:55], v[192:195], v[184:187], v[52:55]
	v_mfma_f32_16x16x32_bf16 v[40:43], v[208:211], v[176:179], v[40:43]
	v_mfma_f32_16x16x32_bf16 v[36:39], v[208:211], v[184:187], v[36:39]
	v_mfma_f32_16x16x32_bf16 v[24:27], v[216:219], v[176:179], v[24:27]
	v_mfma_f32_16x16x32_bf16 v[20:23], v[216:219], v[184:187], v[20:23]
	v_mfma_f32_16x16x32_bf16 v[6:9], v[224:227], v[176:179], v[8:11]
	v_mfma_f32_16x16x32_bf16 v[2:5], v[224:227], v[184:187], v[2:5]
	v_mfma_f32_16x16x32_bf16 v[56:59], v[196:199], v[180:183], v[56:59]
	v_mfma_f32_16x16x32_bf16 v[52:55], v[196:199], v[188:191], v[52:55]
	v_mfma_f32_16x16x32_bf16 v[40:43], v[212:215], v[180:183], v[40:43]
	v_mfma_f32_16x16x32_bf16 v[36:39], v[212:215], v[188:191], v[36:39]
	v_mfma_f32_16x16x32_bf16 v[24:27], v[220:223], v[180:183], v[24:27]
	v_mfma_f32_16x16x32_bf16 v[20:23], v[220:223], v[188:191], v[20:23]
	v_mfma_f32_16x16x32_bf16 v[8:11], v[228:231], v[180:183], v[6:9]
	v_mfma_f32_16x16x32_bf16 v[4:7], v[228:231], v[188:191], v[2:5]
	s_setprio 0
	s_barrier
	s_add_i32 s50, s50, 2
	s_add_u32 s64, s64, 0x100
	s_addc_u32 s65, s65, 0
	s_cmp_gt_u32 s50, 29
	s_cbranch_scc1 .LBB0_1604
.LBB0_1602:
	s_cmpk_lg_i32 s64, 0x800
	s_cbranch_scc1 .LBB0_1601
	v_and_b32_e32 v141, -16, v140
	v_and_b32_e32 v0, 12, v142
	v_or_b32_e32 v141, v141, v0
	v_and_b32_e32 v0, -32, v142
	v_and_or_b32 v0, v140, 15, v0
	v_lshlrev_b32_e32 v0, 1, v0
	v_lshl_add_u32 v141, v141, 13, v0
	v_add_u32_e32 v143, 0x1000, v141
	s_mov_b64 s[0:1], s[14:15]
	global_load_ushort v148, v141, s[0:1]
	global_load_ushort v149, v141, s[0:1] offset:32
	global_load_ushort v150, v141, s[0:1] offset:256
	global_load_ushort v151, v141, s[0:1] offset:288
	global_load_ushort v158, v143, s[0:1]
	global_load_ushort v159, v143, s[0:1] offset:32
	global_load_ushort v160, v143, s[0:1] offset:256
	global_load_ushort v161, v143, s[0:1] offset:288
	s_add_u32 s0, s0, 0x2000
	s_addc_u32 s1, s1, 0
	global_load_ushort v162, v141, s[0:1]
	global_load_ushort v163, v141, s[0:1] offset:32
	global_load_ushort v164, v141, s[0:1] offset:256
	global_load_ushort v165, v141, s[0:1] offset:288
	global_load_ushort v166, v143, s[0:1]
	global_load_ushort v167, v143, s[0:1] offset:32
	global_load_ushort v168, v143, s[0:1] offset:256
	global_load_ushort v169, v143, s[0:1] offset:288
	s_add_u32 s0, s0, 0x2000
	s_addc_u32 s1, s1, 0
	global_load_ushort v176, v141, s[0:1]
	global_load_ushort v177, v141, s[0:1] offset:32
	global_load_ushort v178, v141, s[0:1] offset:256
	global_load_ushort v179, v141, s[0:1] offset:288
	global_load_ushort v180, v143, s[0:1]
	global_load_ushort v181, v143, s[0:1] offset:32
	global_load_ushort v182, v143, s[0:1] offset:256
	global_load_ushort v183, v143, s[0:1] offset:288
	s_add_u32 s0, s0, 0x2000
	s_addc_u32 s1, s1, 0
	global_load_ushort v184, v141, s[0:1]
	global_load_ushort v185, v141, s[0:1] offset:32
	global_load_ushort v186, v141, s[0:1] offset:256
	global_load_ushort v187, v141, s[0:1] offset:288
	global_load_ushort v188, v143, s[0:1]
	global_load_ushort v189, v143, s[0:1] offset:32
	global_load_ushort v190, v143, s[0:1] offset:256
	global_load_ushort v191, v143, s[0:1] offset:288
	s_add_u32 s0, s0, 0x1a000
	s_addc_u32 s1, s1, 0
	s_waitcnt vmcnt(16)
;     static __device__ __forceinline__ pg8::f32x4 up4(pg8::u32x2 a) { return (pg8::f32x4){__uint_as_float(a.x << 16), __uint_as_float(a.x & 0xffff0000u), __uint_as_float(a.y << 16), __uint_as_float(a.y & 0xffff0000u)}; }
;     __device__ __forceinline__ void mid(pg8::f32x4 (&acc)[2][2][4][2], const pg8::Unit& u, int wr, int wc, int fr, int fq) const {
;         int row0 = u.pm * 256 + wr * 64 + fr, col0 = u.pn * 256 + wc * 32 + 4 * fq;
;         asm volatile("" : "+v"(row0), "+v"(col0));
; #pragma unroll
;         for (int ai = 0; ai < 2; ++ai)
; #pragma unroll
;             for (int m = 0; m < 4; ++m) { const bf16* ap = AM + (size_t)(row0 + ai * 128 + m * 16) * 4096 + col0;
; #pragma unroll
;                 for (int bj = 0; bj < 2; ++bj)
; #pragma unroll
;                     for (int n = 0; n < 2; ++n) { const int c = bj * 128 + n * 16;
;                         const pg8::f32x4 a0 = up4(*(const pg8::u32x2*)(ap + c)), a1 = up4(*(const pg8::u32x2*)(ap + 2048 + c));
;                         pg8::f32x4 r; r[0] = a0[0] * __builtin_amdgcn_rcpf(fmaxf(a1[0], 1e-30f)); r[1] = a0[1] * __builtin_amdgcn_rcpf(fmaxf(a1[1], 1e-30f)); r[2] = a0[2] * __builtin_amdgcn_rcpf(fmaxf(a1[2], 1e-30f)); r[3] = a0[3] * __builtin_amdgcn_rcpf(fmaxf(a1[3], 1e-30f));
;                         acc[ai][bj][m][n] = acc[ai][bj][m][n] * r; }
;                 asm volatile("" ::: "memory"); }
	v_lshlrev_b32_e32 v158, 16, v158
	v_lshlrev_b32_e32 v159, 16, v159
	v_lshlrev_b32_e32 v160, 16, v160
	v_lshlrev_b32_e32 v161, 16, v161
	v_max_f32_e32 v158, 0xda24260, v158
	v_max_f32_e32 v159, 0xda24260, v159
	v_max_f32_e32 v160, 0xda24260, v160
	v_max_f32_e32 v161, 0xda24260, v161
	v_rcp_f32_e32 v158, v158
	v_rcp_f32_e32 v159, v159
	v_rcp_f32_e32 v160, v160
	v_rcp_f32_e32 v161, v161
	v_lshlrev_b32_e32 v148, 16, v148
	v_lshlrev_b32_e32 v149, 16, v149
	v_lshlrev_b32_e32 v150, 16, v150
	v_lshlrev_b32_e32 v151, 16, v151
	v_mul_f32_e32 v148, v158, v148
	v_mul_f32_e32 v149, v159, v149
	v_mul_f32_e32 v150, v160, v150
	v_mul_f32_e32 v151, v161, v151
	v_mul_f32_e32 v128, v128, v148
	v_mul_f32_e32 v124, v124, v149
	v_mul_f32_e32 v120, v120, v150
	v_mul_f32_e32 v116, v116, v151
	v_lshlrev_b32_e32 v166, 16, v166
	v_lshlrev_b32_e32 v167, 16, v167
	v_lshlrev_b32_e32 v168, 16, v168
	v_lshlrev_b32_e32 v169, 16, v169
	v_max_f32_e32 v166, 0xda24260, v166
	v_max_f32_e32 v167, 0xda24260, v167
	v_max_f32_e32 v168, 0xda24260, v168
	v_max_f32_e32 v169, 0xda24260, v169
	v_rcp_f32_e32 v166, v166
	v_rcp_f32_e32 v167, v167
	v_rcp_f32_e32 v168, v168
	v_rcp_f32_e32 v169, v169
	v_lshlrev_b32_e32 v162, 16, v162
	v_lshlrev_b32_e32 v163, 16, v163
	v_lshlrev_b32_e32 v164, 16, v164
	v_lshlrev_b32_e32 v165, 16, v165
	v_mul_f32_e32 v162, v166, v162
	v_mul_f32_e32 v163, v167, v163
	v_mul_f32_e32 v164, v168, v164
	v_mul_f32_e32 v165, v169, v165
	v_mul_f32_e32 v129, v129, v162
	v_mul_f32_e32 v125, v125, v163
	v_mul_f32_e32 v121, v121, v164
	v_mul_f32_e32 v117, v117, v165
	global_load_ushort v148, v141, s[0:1]
	global_load_ushort v149, v141, s[0:1] offset:32
	global_load_ushort v150, v141, s[0:1] offset:256
	global_load_ushort v151, v141, s[0:1] offset:288
	global_load_ushort v158, v143, s[0:1]
	global_load_ushort v159, v143, s[0:1] offset:32
	global_load_ushort v160, v143, s[0:1] offset:256
	global_load_ushort v161, v143, s[0:1] offset:288
	s_add_u32 s0, s0, 0x2000
	s_addc_u32 s1, s1, 0
	global_load_ushort v162, v141, s[0:1]
	global_load_ushort v163, v141, s[0:1] offset:32
	global_load_ushort v164, v141, s[0:1] offset:256
	global_load_ushort v165, v141, s[0:1] offset:288
	global_load_ushort v166, v143, s[0:1]
	global_load_ushort v167, v143, s[0:1] offset:32
	global_load_ushort v168, v143, s[0:1] offset:256
	global_load_ushort v169, v143, s[0:1] offset:288
	s_add_u32 s0, s0, 0x2000
	s_addc_u32 s1, s1, 0
	s_waitcnt vmcnt(16)
	v_lshlrev_b32_e32 v180, 16, v180
	v_lshlrev_b32_e32 v181, 16, v181
	v_lshlrev_b32_e32 v182, 16, v182
	v_lshlrev_b32_e32 v183, 16, v183
	v_max_f32_e32 v180, 0xda24260, v180
	v_max_f32_e32 v181, 0xda24260, v181
	v_max_f32_e32 v182, 0xda24260, v182
	v_max_f32_e32 v183, 0xda24260, v183
	v_rcp_f32_e32 v180, v180
	v_rcp_f32_e32 v181, v181
	v_rcp_f32_e32 v182, v182
	v_rcp_f32_e32 v183, v183
	v_lshlrev_b32_e32 v176, 16, v176
	v_lshlrev_b32_e32 v177, 16, v177
	v_lshlrev_b32_e32 v178, 16, v178
	v_lshlrev_b32_e32 v179, 16, v179
	v_mul_f32_e32 v176, v180, v176
	v_mul_f32_e32 v177, v181, v177
	v_mul_f32_e32 v178, v182, v178
	v_mul_f32_e32 v179, v183, v179
	v_mul_f32_e32 v130, v130, v176
	v_mul_f32_e32 v126, v126, v177
	v_mul_f32_e32 v122, v122, v178
	v_mul_f32_e32 v118, v118, v179
	v_lshlrev_b32_e32 v188, 16, v188
	v_lshlrev_b32_e32 v189, 16, v189
	v_lshlrev_b32_e32 v190, 16, v190
	v_lshlrev_b32_e32 v191, 16, v191
	v_max_f32_e32 v188, 0xda24260, v188
	v_max_f32_e32 v189, 0xda24260, v189
	v_max_f32_e32 v190, 0xda24260, v190
	v_max_f32_e32 v191, 0xda24260, v191
	v_rcp_f32_e32 v188, v188
	v_rcp_f32_e32 v189, v189
	v_rcp_f32_e32 v190, v190
	v_rcp_f32_e32 v191, v191
	v_lshlrev_b32_e32 v184, 16, v184
	v_lshlrev_b32_e32 v185, 16, v185
	v_lshlrev_b32_e32 v186, 16, v186
	v_lshlrev_b32_e32 v187, 16, v187
	v_mul_f32_e32 v184, v188, v184
	v_mul_f32_e32 v185, v189, v185
	v_mul_f32_e32 v186, v190, v186
	v_mul_f32_e32 v187, v191, v187
	v_mul_f32_e32 v131, v131, v184
	v_mul_f32_e32 v127, v127, v185
	v_mul_f32_e32 v123, v123, v186
	v_mul_f32_e32 v119, v119, v187
	global_load_ushort v176, v141, s[0:1]
	global_load_ushort v177, v141, s[0:1] offset:32
	global_load_ushort v178, v141, s[0:1] offset:256
	global_load_ushort v179, v141, s[0:1] offset:288
	global_load_ushort v180, v143, s[0:1]
	global_load_ushort v181, v143, s[0:1] offset:32
	global_load_ushort v182, v143, s[0:1] offset:256
	global_load_ushort v183, v143, s[0:1] offset:288
	s_add_u32 s0, s0, 0x2000
	s_addc_u32 s1, s1, 0
	global_load_ushort v184, v141, s[0:1]
	global_load_ushort v185, v141, s[0:1] offset:32
	global_load_ushort v186, v141, s[0:1] offset:256
	global_load_ushort v187, v141, s[0:1] offset:288
	global_load_ushort v188, v143, s[0:1]
	global_load_ushort v189, v143, s[0:1] offset:32
	global_load_ushort v190, v143, s[0:1] offset:256
	global_load_ushort v191, v143, s[0:1] offset:288
	s_add_u32 s0, s0, 0x1a000
	s_addc_u32 s1, s1, 0
	s_waitcnt vmcnt(16)
;     static __device__ __forceinline__ pg8::f32x4 up4(pg8::u32x2 a) { return (pg8::f32x4){__uint_as_float(a.x << 16), __uint_as_float(a.x & 0xffff0000u), __uint_as_float(a.y << 16), __uint_as_float(a.y & 0xffff0000u)}; }
;     __device__ __forceinline__ void mid(pg8::f32x4 (&acc)[2][2][4][2], const pg8::Unit& u, int wr, int wc, int fr, int fq) const {
;         int row0 = u.pm * 256 + wr * 64 + fr, col0 = u.pn * 256 + wc * 32 + 4 * fq;
;         asm volatile("" : "+v"(row0), "+v"(col0));
; #pragma unroll
;         for (int ai = 0; ai < 2; ++ai)
; #pragma unroll
;             for (int m = 0; m < 4; ++m) { const bf16* ap = AM + (size_t)(row0 + ai * 128 + m * 16) * 4096 + col0;
; #pragma unroll
;                 for (int bj = 0; bj < 2; ++bj)
; #pragma unroll
;                     for (int n = 0; n < 2; ++n) { const int c = bj * 128 + n * 16;
;                         const pg8::f32x4 a0 = up4(*(const pg8::u32x2*)(ap + c)), a1 = up4(*(const pg8::u32x2*)(ap + 2048 + c));
;                         pg8::f32x4 r; r[0] = a0[0] * __builtin_amdgcn_rcpf(fmaxf(a1[0], 1e-30f)); r[1] = a0[1] * __builtin_amdgcn_rcpf(fmaxf(a1[1], 1e-30f)); r[2] = a0[2] * __builtin_amdgcn_rcpf(fmaxf(a1[2], 1e-30f)); r[3] = a0[3] * __builtin_amdgcn_rcpf(fmaxf(a1[3], 1e-30f));
;                         acc[ai][bj][m][n] = acc[ai][bj][m][n] * r; }
;                 asm volatile("" ::: "memory"); }
	v_lshlrev_b32_e32 v158, 16, v158
	v_lshlrev_b32_e32 v159, 16, v159
	v_lshlrev_b32_e32 v160, 16, v160
	v_lshlrev_b32_e32 v161, 16, v161
	v_max_f32_e32 v158, 0xda24260, v158
	v_max_f32_e32 v159, 0xda24260, v159
	v_max_f32_e32 v160, 0xda24260, v160
	v_max_f32_e32 v161, 0xda24260, v161
	v_rcp_f32_e32 v158, v158
	v_rcp_f32_e32 v159, v159
	v_rcp_f32_e32 v160, v160
	v_rcp_f32_e32 v161, v161
	v_lshlrev_b32_e32 v148, 16, v148
	v_lshlrev_b32_e32 v149, 16, v149
	v_lshlrev_b32_e32 v150, 16, v150
	v_lshlrev_b32_e32 v151, 16, v151
	v_mul_f32_e32 v148, v158, v148
	v_mul_f32_e32 v149, v159, v149
	v_mul_f32_e32 v150, v160, v150
	v_mul_f32_e32 v151, v161, v151
	v_mul_f32_e32 v112, v112, v148
	v_mul_f32_e32 v108, v108, v149
	v_mul_f32_e32 v104, v104, v150
	v_mul_f32_e32 v100, v100, v151
	v_lshlrev_b32_e32 v166, 16, v166
	v_lshlrev_b32_e32 v167, 16, v167
	v_lshlrev_b32_e32 v168, 16, v168
	v_lshlrev_b32_e32 v169, 16, v169
	v_max_f32_e32 v166, 0xda24260, v166
	v_max_f32_e32 v167, 0xda24260, v167
	v_max_f32_e32 v168, 0xda24260, v168
	v_max_f32_e32 v169, 0xda24260, v169
	v_rcp_f32_e32 v166, v166
	v_rcp_f32_e32 v167, v167
	v_rcp_f32_e32 v168, v168
	v_rcp_f32_e32 v169, v169
	v_lshlrev_b32_e32 v162, 16, v162
	v_lshlrev_b32_e32 v163, 16, v163
	v_lshlrev_b32_e32 v164, 16, v164
	v_lshlrev_b32_e32 v165, 16, v165
	v_mul_f32_e32 v162, v166, v162
	v_mul_f32_e32 v163, v167, v163
	v_mul_f32_e32 v164, v168, v164
	v_mul_f32_e32 v165, v169, v165
	v_mul_f32_e32 v113, v113, v162
	v_mul_f32_e32 v109, v109, v163
	v_mul_f32_e32 v105, v105, v164
	v_mul_f32_e32 v101, v101, v165
	global_load_ushort v148, v141, s[0:1]
	global_load_ushort v149, v141, s[0:1] offset:32
	global_load_ushort v150, v141, s[0:1] offset:256
	global_load_ushort v151, v141, s[0:1] offset:288
	global_load_ushort v158, v143, s[0:1]
	global_load_ushort v159, v143, s[0:1] offset:32
	global_load_ushort v160, v143, s[0:1] offset:256
	global_load_ushort v161, v143, s[0:1] offset:288
	s_add_u32 s0, s0, 0x2000
	s_addc_u32 s1, s1, 0
	global_load_ushort v162, v141, s[0:1]
	global_load_ushort v163, v141, s[0:1] offset:32
	global_load_ushort v164, v141, s[0:1] offset:256
	global_load_ushort v165, v141, s[0:1] offset:288
	global_load_ushort v166, v143, s[0:1]
	global_load_ushort v167, v143, s[0:1] offset:32
	global_load_ushort v168, v143, s[0:1] offset:256
	global_load_ushort v169, v143, s[0:1] offset:288
	s_add_u32 s0, s0, 0x2000
	s_addc_u32 s1, s1, 0
	s_waitcnt vmcnt(16)
	v_lshlrev_b32_e32 v180, 16, v180
	v_lshlrev_b32_e32 v181, 16, v181
	v_lshlrev_b32_e32 v182, 16, v182
	v_lshlrev_b32_e32 v183, 16, v183
	v_max_f32_e32 v180, 0xda24260, v180
	v_max_f32_e32 v181, 0xda24260, v181
	v_max_f32_e32 v182, 0xda24260, v182
	v_max_f32_e32 v183, 0xda24260, v183
	v_rcp_f32_e32 v180, v180
	v_rcp_f32_e32 v181, v181
	v_rcp_f32_e32 v182, v182
	v_rcp_f32_e32 v183, v183
	v_lshlrev_b32_e32 v176, 16, v176
	v_lshlrev_b32_e32 v177, 16, v177
	v_lshlrev_b32_e32 v178, 16, v178
	v_lshlrev_b32_e32 v179, 16, v179
	v_mul_f32_e32 v176, v180, v176
	v_mul_f32_e32 v177, v181, v177
	v_mul_f32_e32 v178, v182, v178
	v_mul_f32_e32 v179, v183, v179
	v_mul_f32_e32 v114, v114, v176
	v_mul_f32_e32 v110, v110, v177
	v_mul_f32_e32 v106, v106, v178
	v_mul_f32_e32 v102, v102, v179
	v_lshlrev_b32_e32 v188, 16, v188
	v_lshlrev_b32_e32 v189, 16, v189
	v_lshlrev_b32_e32 v190, 16, v190
	v_lshlrev_b32_e32 v191, 16, v191
	v_max_f32_e32 v188, 0xda24260, v188
	v_max_f32_e32 v189, 0xda24260, v189
	v_max_f32_e32 v190, 0xda24260, v190
	v_max_f32_e32 v191, 0xda24260, v191
	v_rcp_f32_e32 v188, v188
	v_rcp_f32_e32 v189, v189
	v_rcp_f32_e32 v190, v190
	v_rcp_f32_e32 v191, v191
	v_lshlrev_b32_e32 v184, 16, v184
	v_lshlrev_b32_e32 v185, 16, v185
	v_lshlrev_b32_e32 v186, 16, v186
	v_lshlrev_b32_e32 v187, 16, v187
	v_mul_f32_e32 v184, v188, v184
	v_mul_f32_e32 v185, v189, v185
	v_mul_f32_e32 v186, v190, v186
	v_mul_f32_e32 v187, v191, v187
	v_mul_f32_e32 v115, v115, v184
	v_mul_f32_e32 v111, v111, v185
	v_mul_f32_e32 v107, v107, v186
	v_mul_f32_e32 v103, v103, v187
	global_load_ushort v176, v141, s[0:1]
	global_load_ushort v177, v141, s[0:1] offset:32
	global_load_ushort v178, v141, s[0:1] offset:256
	global_load_ushort v179, v141, s[0:1] offset:288
	global_load_ushort v180, v143, s[0:1]
	global_load_ushort v181, v143, s[0:1] offset:32
	global_load_ushort v182, v143, s[0:1] offset:256
	global_load_ushort v183, v143, s[0:1] offset:288
	s_add_u32 s0, s0, 0x2000
	s_addc_u32 s1, s1, 0
	global_load_ushort v184, v141, s[0:1]
	global_load_ushort v185, v141, s[0:1] offset:32
	global_load_ushort v186, v141, s[0:1] offset:256
	global_load_ushort v187, v141, s[0:1] offset:288
	global_load_ushort v188, v143, s[0:1]
	global_load_ushort v189, v143, s[0:1] offset:32
	global_load_ushort v190, v143, s[0:1] offset:256
	global_load_ushort v191, v143, s[0:1] offset:288
	s_add_u32 s0, s0, 0x1a000
	s_addc_u32 s1, s1, 0
	s_waitcnt vmcnt(16)
;     static __device__ __forceinline__ pg8::f32x4 up4(pg8::u32x2 a) { return (pg8::f32x4){__uint_as_float(a.x << 16), __uint_as_float(a.x & 0xffff0000u), __uint_as_float(a.y << 16), __uint_as_float(a.y & 0xffff0000u)}; }
;     __device__ __forceinline__ void mid(pg8::f32x4 (&acc)[2][2][4][2], const pg8::Unit& u, int wr, int wc, int fr, int fq) const {
;         int row0 = u.pm * 256 + wr * 64 + fr, col0 = u.pn * 256 + wc * 32 + 4 * fq;
;         asm volatile("" : "+v"(row0), "+v"(col0));
; #pragma unroll
;         for (int ai = 0; ai < 2; ++ai)
; #pragma unroll
;             for (int m = 0; m < 4; ++m) { const bf16* ap = AM + (size_t)(row0 + ai * 128 + m * 16) * 4096 + col0;
; #pragma unroll
;                 for (int bj = 0; bj < 2; ++bj)
; #pragma unroll
;                     for (int n = 0; n < 2; ++n) { const int c = bj * 128 + n * 16;
;                         const pg8::f32x4 a0 = up4(*(const pg8::u32x2*)(ap + c)), a1 = up4(*(const pg8::u32x2*)(ap + 2048 + c));
;                         pg8::f32x4 r; r[0] = a0[0] * __builtin_amdgcn_rcpf(fmaxf(a1[0], 1e-30f)); r[1] = a0[1] * __builtin_amdgcn_rcpf(fmaxf(a1[1], 1e-30f)); r[2] = a0[2] * __builtin_amdgcn_rcpf(fmaxf(a1[2], 1e-30f)); r[3] = a0[3] * __builtin_amdgcn_rcpf(fmaxf(a1[3], 1e-30f));
;                         acc[ai][bj][m][n] = acc[ai][bj][m][n] * r; }
;                 asm volatile("" ::: "memory"); }
	v_lshlrev_b32_e32 v158, 16, v158
	v_lshlrev_b32_e32 v159, 16, v159
	v_lshlrev_b32_e32 v160, 16, v160
	v_lshlrev_b32_e32 v161, 16, v161
	v_max_f32_e32 v158, 0xda24260, v158
	v_max_f32_e32 v159, 0xda24260, v159
	v_max_f32_e32 v160, 0xda24260, v160
	v_max_f32_e32 v161, 0xda24260, v161
	v_rcp_f32_e32 v158, v158
	v_rcp_f32_e32 v159, v159
	v_rcp_f32_e32 v160, v160
	v_rcp_f32_e32 v161, v161
	v_lshlrev_b32_e32 v148, 16, v148
	v_lshlrev_b32_e32 v149, 16, v149
	v_lshlrev_b32_e32 v150, 16, v150
	v_lshlrev_b32_e32 v151, 16, v151
	v_mul_f32_e32 v148, v158, v148
	v_mul_f32_e32 v149, v159, v149
	v_mul_f32_e32 v150, v160, v150
	v_mul_f32_e32 v151, v161, v151
	v_mul_f32_e32 v96, v96, v148
	v_mul_f32_e32 v92, v92, v149
	v_mul_f32_e32 v88, v88, v150
	v_mul_f32_e32 v84, v84, v151
	v_lshlrev_b32_e32 v166, 16, v166
	v_lshlrev_b32_e32 v167, 16, v167
	v_lshlrev_b32_e32 v168, 16, v168
	v_lshlrev_b32_e32 v169, 16, v169
	v_max_f32_e32 v166, 0xda24260, v166
	v_max_f32_e32 v167, 0xda24260, v167
	v_max_f32_e32 v168, 0xda24260, v168
	v_max_f32_e32 v169, 0xda24260, v169
	v_rcp_f32_e32 v166, v166
	v_rcp_f32_e32 v167, v167
	v_rcp_f32_e32 v168, v168
	v_rcp_f32_e32 v169, v169
	v_lshlrev_b32_e32 v162, 16, v162
	v_lshlrev_b32_e32 v163, 16, v163
	v_lshlrev_b32_e32 v164, 16, v164
	v_lshlrev_b32_e32 v165, 16, v165
	v_mul_f32_e32 v162, v166, v162
	v_mul_f32_e32 v163, v167, v163
	v_mul_f32_e32 v164, v168, v164
	v_mul_f32_e32 v165, v169, v165
	v_mul_f32_e32 v97, v97, v162
	v_mul_f32_e32 v93, v93, v163
	v_mul_f32_e32 v89, v89, v164
	v_mul_f32_e32 v85, v85, v165
	global_load_ushort v148, v141, s[0:1]
	global_load_ushort v149, v141, s[0:1] offset:32
	global_load_ushort v150, v141, s[0:1] offset:256
	global_load_ushort v151, v141, s[0:1] offset:288
	global_load_ushort v158, v143, s[0:1]
	global_load_ushort v159, v143, s[0:1] offset:32
	global_load_ushort v160, v143, s[0:1] offset:256
	global_load_ushort v161, v143, s[0:1] offset:288
	s_add_u32 s0, s0, 0x2000
	s_addc_u32 s1, s1, 0
	global_load_ushort v162, v141, s[0:1]
	global_load_ushort v163, v141, s[0:1] offset:32
	global_load_ushort v164, v141, s[0:1] offset:256
	global_load_ushort v165, v141, s[0:1] offset:288
	global_load_ushort v166, v143, s[0:1]
	global_load_ushort v167, v143, s[0:1] offset:32
	global_load_ushort v168, v143, s[0:1] offset:256
	global_load_ushort v169, v143, s[0:1] offset:288
	s_add_u32 s0, s0, 0x2000
	s_addc_u32 s1, s1, 0
	s_waitcnt vmcnt(16)
	v_lshlrev_b32_e32 v180, 16, v180
	v_lshlrev_b32_e32 v181, 16, v181
	v_lshlrev_b32_e32 v182, 16, v182
	v_lshlrev_b32_e32 v183, 16, v183
	v_max_f32_e32 v180, 0xda24260, v180
	v_max_f32_e32 v181, 0xda24260, v181
	v_max_f32_e32 v182, 0xda24260, v182
	v_max_f32_e32 v183, 0xda24260, v183
	v_rcp_f32_e32 v180, v180
	v_rcp_f32_e32 v181, v181
	v_rcp_f32_e32 v182, v182
	v_rcp_f32_e32 v183, v183
	v_lshlrev_b32_e32 v176, 16, v176
	v_lshlrev_b32_e32 v177, 16, v177
	v_lshlrev_b32_e32 v178, 16, v178
	v_lshlrev_b32_e32 v179, 16, v179
	v_mul_f32_e32 v176, v180, v176
	v_mul_f32_e32 v177, v181, v177
	v_mul_f32_e32 v178, v182, v178
	v_mul_f32_e32 v179, v183, v179
	v_mul_f32_e32 v98, v98, v176
	v_mul_f32_e32 v94, v94, v177
	v_mul_f32_e32 v90, v90, v178
	v_mul_f32_e32 v86, v86, v179
	v_lshlrev_b32_e32 v188, 16, v188
	v_lshlrev_b32_e32 v189, 16, v189
	v_lshlrev_b32_e32 v190, 16, v190
	v_lshlrev_b32_e32 v191, 16, v191
	v_max_f32_e32 v188, 0xda24260, v188
	v_max_f32_e32 v189, 0xda24260, v189
	v_max_f32_e32 v190, 0xda24260, v190
	v_max_f32_e32 v191, 0xda24260, v191
	v_rcp_f32_e32 v188, v188
	v_rcp_f32_e32 v189, v189
	v_rcp_f32_e32 v190, v190
	v_rcp_f32_e32 v191, v191
	v_lshlrev_b32_e32 v184, 16, v184
	v_lshlrev_b32_e32 v185, 16, v185
	v_lshlrev_b32_e32 v186, 16, v186
	v_lshlrev_b32_e32 v187, 16, v187
	v_mul_f32_e32 v184, v188, v184
	v_mul_f32_e32 v185, v189, v185
	v_mul_f32_e32 v186, v190, v186
	v_mul_f32_e32 v187, v191, v187
	v_mul_f32_e32 v99, v99, v184
	v_mul_f32_e32 v95, v95, v185
	v_mul_f32_e32 v91, v91, v186
	v_mul_f32_e32 v87, v87, v187
	global_load_ushort v176, v141, s[0:1]
	global_load_ushort v177, v141, s[0:1] offset:32
	global_load_ushort v178, v141, s[0:1] offset:256
	global_load_ushort v179, v141, s[0:1] offset:288
	global_load_ushort v180, v143, s[0:1]
	global_load_ushort v181, v143, s[0:1] offset:32
	global_load_ushort v182, v143, s[0:1] offset:256
	global_load_ushort v183, v143, s[0:1] offset:288
	s_add_u32 s0, s0, 0x2000
	s_addc_u32 s1, s1, 0
	global_load_ushort v184, v141, s[0:1]
	global_load_ushort v185, v141, s[0:1] offset:32
	global_load_ushort v186, v141, s[0:1] offset:256
	global_load_ushort v187, v141, s[0:1] offset:288
	global_load_ushort v188, v143, s[0:1]
	global_load_ushort v189, v143, s[0:1] offset:32
	global_load_ushort v190, v143, s[0:1] offset:256
	global_load_ushort v191, v143, s[0:1] offset:288
	s_add_u32 s0, s0, 0x9a000
	s_addc_u32 s1, s1, 0
	s_waitcnt vmcnt(16)
;     static __device__ __forceinline__ pg8::f32x4 up4(pg8::u32x2 a) { return (pg8::f32x4){__uint_as_float(a.x << 16), __uint_as_float(a.x & 0xffff0000u), __uint_as_float(a.y << 16), __uint_as_float(a.y & 0xffff0000u)}; }
;     __device__ __forceinline__ void mid(pg8::f32x4 (&acc)[2][2][4][2], const pg8::Unit& u, int wr, int wc, int fr, int fq) const {
;         int row0 = u.pm * 256 + wr * 64 + fr, col0 = u.pn * 256 + wc * 32 + 4 * fq;
;         asm volatile("" : "+v"(row0), "+v"(col0));
; #pragma unroll
;         for (int ai = 0; ai < 2; ++ai)
; #pragma unroll
;             for (int m = 0; m < 4; ++m) { const bf16* ap = AM + (size_t)(row0 + ai * 128 + m * 16) * 4096 + col0;
; #pragma unroll
;                 for (int bj = 0; bj < 2; ++bj)
; #pragma unroll
;                     for (int n = 0; n < 2; ++n) { const int c = bj * 128 + n * 16;
;                         const pg8::f32x4 a0 = up4(*(const pg8::u32x2*)(ap + c)), a1 = up4(*(const pg8::u32x2*)(ap + 2048 + c));
;                         pg8::f32x4 r; r[0] = a0[0] * __builtin_amdgcn_rcpf(fmaxf(a1[0], 1e-30f)); r[1] = a0[1] * __builtin_amdgcn_rcpf(fmaxf(a1[1], 1e-30f)); r[2] = a0[2] * __builtin_amdgcn_rcpf(fmaxf(a1[2], 1e-30f)); r[3] = a0[3] * __builtin_amdgcn_rcpf(fmaxf(a1[3], 1e-30f));
;                         acc[ai][bj][m][n] = acc[ai][bj][m][n] * r; }
;                 asm volatile("" ::: "memory"); }
	v_lshlrev_b32_e32 v158, 16, v158
	v_lshlrev_b32_e32 v159, 16, v159
	v_lshlrev_b32_e32 v160, 16, v160
	v_lshlrev_b32_e32 v161, 16, v161
	v_max_f32_e32 v158, 0xda24260, v158
	v_max_f32_e32 v159, 0xda24260, v159
	v_max_f32_e32 v160, 0xda24260, v160
	v_max_f32_e32 v161, 0xda24260, v161
	v_rcp_f32_e32 v158, v158
	v_rcp_f32_e32 v159, v159
	v_rcp_f32_e32 v160, v160
	v_rcp_f32_e32 v161, v161
	v_lshlrev_b32_e32 v148, 16, v148
	v_lshlrev_b32_e32 v149, 16, v149
	v_lshlrev_b32_e32 v150, 16, v150
	v_lshlrev_b32_e32 v151, 16, v151
	v_mul_f32_e32 v148, v158, v148
	v_mul_f32_e32 v149, v159, v149
	v_mul_f32_e32 v150, v160, v150
	v_mul_f32_e32 v151, v161, v151
	v_mul_f32_e32 v80, v80, v148
	v_mul_f32_e32 v76, v76, v149
	v_mul_f32_e32 v72, v72, v150
	v_mul_f32_e32 v68, v68, v151
	v_lshlrev_b32_e32 v166, 16, v166
	v_lshlrev_b32_e32 v167, 16, v167
	v_lshlrev_b32_e32 v168, 16, v168
	v_lshlrev_b32_e32 v169, 16, v169
	v_max_f32_e32 v166, 0xda24260, v166
	v_max_f32_e32 v167, 0xda24260, v167
	v_max_f32_e32 v168, 0xda24260, v168
	v_max_f32_e32 v169, 0xda24260, v169
	v_rcp_f32_e32 v166, v166
	v_rcp_f32_e32 v167, v167
	v_rcp_f32_e32 v168, v168
	v_rcp_f32_e32 v169, v169
	v_lshlrev_b32_e32 v162, 16, v162
	v_lshlrev_b32_e32 v163, 16, v163
	v_lshlrev_b32_e32 v164, 16, v164
	v_lshlrev_b32_e32 v165, 16, v165
	v_mul_f32_e32 v162, v166, v162
	v_mul_f32_e32 v163, v167, v163
	v_mul_f32_e32 v164, v168, v164
	v_mul_f32_e32 v165, v169, v165
	v_mul_f32_e32 v81, v81, v162
	v_mul_f32_e32 v77, v77, v163
	v_mul_f32_e32 v73, v73, v164
	v_mul_f32_e32 v69, v69, v165
	global_load_ushort v148, v141, s[0:1]
	global_load_ushort v149, v141, s[0:1] offset:32
	global_load_ushort v150, v141, s[0:1] offset:256
	global_load_ushort v151, v141, s[0:1] offset:288
	global_load_ushort v158, v143, s[0:1]
	global_load_ushort v159, v143, s[0:1] offset:32
	global_load_ushort v160, v143, s[0:1] offset:256
	global_load_ushort v161, v143, s[0:1] offset:288
	s_add_u32 s0, s0, 0x2000
	s_addc_u32 s1, s1, 0
	global_load_ushort v162, v141, s[0:1]
	global_load_ushort v163, v141, s[0:1] offset:32
	global_load_ushort v164, v141, s[0:1] offset:256
	global_load_ushort v165, v141, s[0:1] offset:288
	global_load_ushort v166, v143, s[0:1]
	global_load_ushort v167, v143, s[0:1] offset:32
	global_load_ushort v168, v143, s[0:1] offset:256
	global_load_ushort v169, v143, s[0:1] offset:288
	s_add_u32 s0, s0, 0x2000
	s_addc_u32 s1, s1, 0
	s_waitcnt vmcnt(16)
	v_lshlrev_b32_e32 v180, 16, v180
	v_lshlrev_b32_e32 v181, 16, v181
	v_lshlrev_b32_e32 v182, 16, v182
	v_lshlrev_b32_e32 v183, 16, v183
	v_max_f32_e32 v180, 0xda24260, v180
	v_max_f32_e32 v181, 0xda24260, v181
	v_max_f32_e32 v182, 0xda24260, v182
	v_max_f32_e32 v183, 0xda24260, v183
	v_rcp_f32_e32 v180, v180
	v_rcp_f32_e32 v181, v181
	v_rcp_f32_e32 v182, v182
	v_rcp_f32_e32 v183, v183
	v_lshlrev_b32_e32 v176, 16, v176
	v_lshlrev_b32_e32 v177, 16, v177
	v_lshlrev_b32_e32 v178, 16, v178
	v_lshlrev_b32_e32 v179, 16, v179
	v_mul_f32_e32 v176, v180, v176
	v_mul_f32_e32 v177, v181, v177
	v_mul_f32_e32 v178, v182, v178
	v_mul_f32_e32 v179, v183, v179
	v_mul_f32_e32 v82, v82, v176
	v_mul_f32_e32 v78, v78, v177
	v_mul_f32_e32 v74, v74, v178
	v_mul_f32_e32 v70, v70, v179
	v_lshlrev_b32_e32 v188, 16, v188
	v_lshlrev_b32_e32 v189, 16, v189
	v_lshlrev_b32_e32 v190, 16, v190
	v_lshlrev_b32_e32 v191, 16, v191
	v_max_f32_e32 v188, 0xda24260, v188
	v_max_f32_e32 v189, 0xda24260, v189
	v_max_f32_e32 v190, 0xda24260, v190
	v_max_f32_e32 v191, 0xda24260, v191
	v_rcp_f32_e32 v188, v188
	v_rcp_f32_e32 v189, v189
	v_rcp_f32_e32 v190, v190
	v_rcp_f32_e32 v191, v191
	v_lshlrev_b32_e32 v184, 16, v184
	v_lshlrev_b32_e32 v185, 16, v185
	v_lshlrev_b32_e32 v186, 16, v186
	v_lshlrev_b32_e32 v187, 16, v187
	v_mul_f32_e32 v184, v188, v184
	v_mul_f32_e32 v185, v189, v185
	v_mul_f32_e32 v186, v190, v186
	v_mul_f32_e32 v187, v191, v187
	v_mul_f32_e32 v83, v83, v184
	v_mul_f32_e32 v79, v79, v185
	v_mul_f32_e32 v75, v75, v186
	v_mul_f32_e32 v71, v71, v187
	global_load_ushort v176, v141, s[0:1]
	global_load_ushort v177, v141, s[0:1] offset:32
	global_load_ushort v178, v141, s[0:1] offset:256
	global_load_ushort v179, v141, s[0:1] offset:288
	global_load_ushort v180, v143, s[0:1]
	global_load_ushort v181, v143, s[0:1] offset:32
	global_load_ushort v182, v143, s[0:1] offset:256
	global_load_ushort v183, v143, s[0:1] offset:288
	s_add_u32 s0, s0, 0x2000
	s_addc_u32 s1, s1, 0
	global_load_ushort v184, v141, s[0:1]
	global_load_ushort v185, v141, s[0:1] offset:32
	global_load_ushort v186, v141, s[0:1] offset:256
	global_load_ushort v187, v141, s[0:1] offset:288
	global_load_ushort v188, v143, s[0:1]
	global_load_ushort v189, v143, s[0:1] offset:32
	global_load_ushort v190, v143, s[0:1] offset:256
	global_load_ushort v191, v143, s[0:1] offset:288
	s_add_u32 s0, s0, 0x1a000
	s_addc_u32 s1, s1, 0
	s_waitcnt vmcnt(16)
;     static __device__ __forceinline__ pg8::f32x4 up4(pg8::u32x2 a) { return (pg8::f32x4){__uint_as_float(a.x << 16), __uint_as_float(a.x & 0xffff0000u), __uint_as_float(a.y << 16), __uint_as_float(a.y & 0xffff0000u)}; }
;     __device__ __forceinline__ void mid(pg8::f32x4 (&acc)[2][2][4][2], const pg8::Unit& u, int wr, int wc, int fr, int fq) const {
;         int row0 = u.pm * 256 + wr * 64 + fr, col0 = u.pn * 256 + wc * 32 + 4 * fq;
;         asm volatile("" : "+v"(row0), "+v"(col0));
; #pragma unroll
;         for (int ai = 0; ai < 2; ++ai)
; #pragma unroll
;             for (int m = 0; m < 4; ++m) { const bf16* ap = AM + (size_t)(row0 + ai * 128 + m * 16) * 4096 + col0;
; #pragma unroll
;                 for (int bj = 0; bj < 2; ++bj)
; #pragma unroll
;                     for (int n = 0; n < 2; ++n) { const int c = bj * 128 + n * 16;
;                         const pg8::f32x4 a0 = up4(*(const pg8::u32x2*)(ap + c)), a1 = up4(*(const pg8::u32x2*)(ap + 2048 + c));
;                         pg8::f32x4 r; r[0] = a0[0] * __builtin_amdgcn_rcpf(fmaxf(a1[0], 1e-30f)); r[1] = a0[1] * __builtin_amdgcn_rcpf(fmaxf(a1[1], 1e-30f)); r[2] = a0[2] * __builtin_amdgcn_rcpf(fmaxf(a1[2], 1e-30f)); r[3] = a0[3] * __builtin_amdgcn_rcpf(fmaxf(a1[3], 1e-30f));
;                         acc[ai][bj][m][n] = acc[ai][bj][m][n] * r; }
;                 asm volatile("" ::: "memory"); }
	v_lshlrev_b32_e32 v158, 16, v158
	v_lshlrev_b32_e32 v159, 16, v159
	v_lshlrev_b32_e32 v160, 16, v160
	v_lshlrev_b32_e32 v161, 16, v161
	v_max_f32_e32 v158, 0xda24260, v158
	v_max_f32_e32 v159, 0xda24260, v159
	v_max_f32_e32 v160, 0xda24260, v160
	v_max_f32_e32 v161, 0xda24260, v161
	v_rcp_f32_e32 v158, v158
	v_rcp_f32_e32 v159, v159
	v_rcp_f32_e32 v160, v160
	v_rcp_f32_e32 v161, v161
	v_lshlrev_b32_e32 v148, 16, v148
	v_lshlrev_b32_e32 v149, 16, v149
	v_lshlrev_b32_e32 v150, 16, v150
	v_lshlrev_b32_e32 v151, 16, v151
	v_mul_f32_e32 v148, v158, v148
	v_mul_f32_e32 v149, v159, v149
	v_mul_f32_e32 v150, v160, v150
	v_mul_f32_e32 v151, v161, v151
	v_mul_f32_e32 v64, v64, v148
	v_mul_f32_e32 v60, v60, v149
	v_mul_f32_e32 v56, v56, v150
	v_mul_f32_e32 v52, v52, v151
	v_lshlrev_b32_e32 v166, 16, v166
	v_lshlrev_b32_e32 v167, 16, v167
	v_lshlrev_b32_e32 v168, 16, v168
	v_lshlrev_b32_e32 v169, 16, v169
	v_max_f32_e32 v166, 0xda24260, v166
	v_max_f32_e32 v167, 0xda24260, v167
	v_max_f32_e32 v168, 0xda24260, v168
	v_max_f32_e32 v169, 0xda24260, v169
	v_rcp_f32_e32 v166, v166
	v_rcp_f32_e32 v167, v167
	v_rcp_f32_e32 v168, v168
	v_rcp_f32_e32 v169, v169
	v_lshlrev_b32_e32 v162, 16, v162
	v_lshlrev_b32_e32 v163, 16, v163
	v_lshlrev_b32_e32 v164, 16, v164
	v_lshlrev_b32_e32 v165, 16, v165
	v_mul_f32_e32 v162, v166, v162
	v_mul_f32_e32 v163, v167, v163
	v_mul_f32_e32 v164, v168, v164
	v_mul_f32_e32 v165, v169, v165
	v_mul_f32_e32 v65, v65, v162
	v_mul_f32_e32 v61, v61, v163
	v_mul_f32_e32 v57, v57, v164
	v_mul_f32_e32 v53, v53, v165
	global_load_ushort v148, v141, s[0:1]
	global_load_ushort v149, v141, s[0:1] offset:32
	global_load_ushort v150, v141, s[0:1] offset:256
	global_load_ushort v151, v141, s[0:1] offset:288
	global_load_ushort v158, v143, s[0:1]
	global_load_ushort v159, v143, s[0:1] offset:32
	global_load_ushort v160, v143, s[0:1] offset:256
	global_load_ushort v161, v143, s[0:1] offset:288
	s_add_u32 s0, s0, 0x2000
	s_addc_u32 s1, s1, 0
	global_load_ushort v162, v141, s[0:1]
	global_load_ushort v163, v141, s[0:1] offset:32
	global_load_ushort v164, v141, s[0:1] offset:256
	global_load_ushort v165, v141, s[0:1] offset:288
	global_load_ushort v166, v143, s[0:1]
	global_load_ushort v167, v143, s[0:1] offset:32
	global_load_ushort v168, v143, s[0:1] offset:256
	global_load_ushort v169, v143, s[0:1] offset:288
	s_add_u32 s0, s0, 0x2000
	s_addc_u32 s1, s1, 0
	s_waitcnt vmcnt(16)
	v_lshlrev_b32_e32 v180, 16, v180
	v_lshlrev_b32_e32 v181, 16, v181
	v_lshlrev_b32_e32 v182, 16, v182
	v_lshlrev_b32_e32 v183, 16, v183
	v_max_f32_e32 v180, 0xda24260, v180
	v_max_f32_e32 v181, 0xda24260, v181
	v_max_f32_e32 v182, 0xda24260, v182
	v_max_f32_e32 v183, 0xda24260, v183
	v_rcp_f32_e32 v180, v180
	v_rcp_f32_e32 v181, v181
	v_rcp_f32_e32 v182, v182
	v_rcp_f32_e32 v183, v183
	v_lshlrev_b32_e32 v176, 16, v176
	v_lshlrev_b32_e32 v177, 16, v177
	v_lshlrev_b32_e32 v178, 16, v178
	v_lshlrev_b32_e32 v179, 16, v179
	v_mul_f32_e32 v176, v180, v176
	v_mul_f32_e32 v177, v181, v177
	v_mul_f32_e32 v178, v182, v178
	v_mul_f32_e32 v179, v183, v179
	v_mul_f32_e32 v66, v66, v176
	v_mul_f32_e32 v62, v62, v177
	v_mul_f32_e32 v58, v58, v178
	v_mul_f32_e32 v54, v54, v179
	v_lshlrev_b32_e32 v188, 16, v188
	v_lshlrev_b32_e32 v189, 16, v189
	v_lshlrev_b32_e32 v190, 16, v190
	v_lshlrev_b32_e32 v191, 16, v191
	v_max_f32_e32 v188, 0xda24260, v188
	v_max_f32_e32 v189, 0xda24260, v189
	v_max_f32_e32 v190, 0xda24260, v190
	v_max_f32_e32 v191, 0xda24260, v191
	v_rcp_f32_e32 v188, v188
	v_rcp_f32_e32 v189, v189
	v_rcp_f32_e32 v190, v190
	v_rcp_f32_e32 v191, v191
	v_lshlrev_b32_e32 v184, 16, v184
	v_lshlrev_b32_e32 v185, 16, v185
	v_lshlrev_b32_e32 v186, 16, v186
	v_lshlrev_b32_e32 v187, 16, v187
	v_mul_f32_e32 v184, v188, v184
	v_mul_f32_e32 v185, v189, v185
	v_mul_f32_e32 v186, v190, v186
	v_mul_f32_e32 v187, v191, v187
	v_mul_f32_e32 v67, v67, v184
	v_mul_f32_e32 v63, v63, v185
	v_mul_f32_e32 v59, v59, v186
	v_mul_f32_e32 v55, v55, v187
	global_load_ushort v176, v141, s[0:1]
	global_load_ushort v177, v141, s[0:1] offset:32
	global_load_ushort v178, v141, s[0:1] offset:256
	global_load_ushort v179, v141, s[0:1] offset:288
	global_load_ushort v180, v143, s[0:1]
	global_load_ushort v181, v143, s[0:1] offset:32
	global_load_ushort v182, v143, s[0:1] offset:256
	global_load_ushort v183, v143, s[0:1] offset:288
	s_add_u32 s0, s0, 0x2000
	s_addc_u32 s1, s1, 0
	global_load_ushort v184, v141, s[0:1]
	global_load_ushort v185, v141, s[0:1] offset:32
	global_load_ushort v186, v141, s[0:1] offset:256
	global_load_ushort v187, v141, s[0:1] offset:288
	global_load_ushort v188, v143, s[0:1]
	global_load_ushort v189, v143, s[0:1] offset:32
	global_load_ushort v190, v143, s[0:1] offset:256
	global_load_ushort v191, v143, s[0:1] offset:288
	s_add_u32 s0, s0, 0x1a000
	s_addc_u32 s1, s1, 0
	s_waitcnt vmcnt(16)
;     static __device__ __forceinline__ pg8::f32x4 up4(pg8::u32x2 a) { return (pg8::f32x4){__uint_as_float(a.x << 16), __uint_as_float(a.x & 0xffff0000u), __uint_as_float(a.y << 16), __uint_as_float(a.y & 0xffff0000u)}; }
;     __device__ __forceinline__ void mid(pg8::f32x4 (&acc)[2][2][4][2], const pg8::Unit& u, int wr, int wc, int fr, int fq) const {
;         int row0 = u.pm * 256 + wr * 64 + fr, col0 = u.pn * 256 + wc * 32 + 4 * fq;
;         asm volatile("" : "+v"(row0), "+v"(col0));
; #pragma unroll
;         for (int ai = 0; ai < 2; ++ai)
; #pragma unroll
;             for (int m = 0; m < 4; ++m) { const bf16* ap = AM + (size_t)(row0 + ai * 128 + m * 16) * 4096 + col0;
; #pragma unroll
;                 for (int bj = 0; bj < 2; ++bj)
; #pragma unroll
;                     for (int n = 0; n < 2; ++n) { const int c = bj * 128 + n * 16;
;                         const pg8::f32x4 a0 = up4(*(const pg8::u32x2*)(ap + c)), a1 = up4(*(const pg8::u32x2*)(ap + 2048 + c));
;                         pg8::f32x4 r; r[0] = a0[0] * __builtin_amdgcn_rcpf(fmaxf(a1[0], 1e-30f)); r[1] = a0[1] * __builtin_amdgcn_rcpf(fmaxf(a1[1], 1e-30f)); r[2] = a0[2] * __builtin_amdgcn_rcpf(fmaxf(a1[2], 1e-30f)); r[3] = a0[3] * __builtin_amdgcn_rcpf(fmaxf(a1[3], 1e-30f));
;                         acc[ai][bj][m][n] = acc[ai][bj][m][n] * r; }
;                 asm volatile("" ::: "memory"); }
	v_lshlrev_b32_e32 v158, 16, v158
	v_lshlrev_b32_e32 v159, 16, v159
	v_lshlrev_b32_e32 v160, 16, v160
	v_lshlrev_b32_e32 v161, 16, v161
	v_max_f32_e32 v158, 0xda24260, v158
	v_max_f32_e32 v159, 0xda24260, v159
	v_max_f32_e32 v160, 0xda24260, v160
	v_max_f32_e32 v161, 0xda24260, v161
	v_rcp_f32_e32 v158, v158
	v_rcp_f32_e32 v159, v159
	v_rcp_f32_e32 v160, v160
	v_rcp_f32_e32 v161, v161
	v_lshlrev_b32_e32 v148, 16, v148
	v_lshlrev_b32_e32 v149, 16, v149
	v_lshlrev_b32_e32 v150, 16, v150
	v_lshlrev_b32_e32 v151, 16, v151
	v_mul_f32_e32 v148, v158, v148
	v_mul_f32_e32 v149, v159, v149
	v_mul_f32_e32 v150, v160, v150
	v_mul_f32_e32 v151, v161, v151
	v_mul_f32_e32 v48, v48, v148
	v_mul_f32_e32 v44, v44, v149
	v_mul_f32_e32 v40, v40, v150
	v_mul_f32_e32 v36, v36, v151
	v_lshlrev_b32_e32 v166, 16, v166
	v_lshlrev_b32_e32 v167, 16, v167
	v_lshlrev_b32_e32 v168, 16, v168
	v_lshlrev_b32_e32 v169, 16, v169
	v_max_f32_e32 v166, 0xda24260, v166
	v_max_f32_e32 v167, 0xda24260, v167
	v_max_f32_e32 v168, 0xda24260, v168
	v_max_f32_e32 v169, 0xda24260, v169
	v_rcp_f32_e32 v166, v166
	v_rcp_f32_e32 v167, v167
	v_rcp_f32_e32 v168, v168
	v_rcp_f32_e32 v169, v169
	v_lshlrev_b32_e32 v162, 16, v162
	v_lshlrev_b32_e32 v163, 16, v163
	v_lshlrev_b32_e32 v164, 16, v164
	v_lshlrev_b32_e32 v165, 16, v165
	v_mul_f32_e32 v162, v166, v162
	v_mul_f32_e32 v163, v167, v163
	v_mul_f32_e32 v164, v168, v164
	v_mul_f32_e32 v165, v169, v165
	v_mul_f32_e32 v49, v49, v162
	v_mul_f32_e32 v45, v45, v163
	v_mul_f32_e32 v41, v41, v164
	v_mul_f32_e32 v37, v37, v165
	global_load_ushort v148, v141, s[0:1]
	global_load_ushort v149, v141, s[0:1] offset:32
	global_load_ushort v150, v141, s[0:1] offset:256
	global_load_ushort v151, v141, s[0:1] offset:288
	global_load_ushort v158, v143, s[0:1]
	global_load_ushort v159, v143, s[0:1] offset:32
	global_load_ushort v160, v143, s[0:1] offset:256
	global_load_ushort v161, v143, s[0:1] offset:288
	s_add_u32 s0, s0, 0x2000
	s_addc_u32 s1, s1, 0
	global_load_ushort v162, v141, s[0:1]
	global_load_ushort v163, v141, s[0:1] offset:32
	global_load_ushort v164, v141, s[0:1] offset:256
	global_load_ushort v165, v141, s[0:1] offset:288
	global_load_ushort v166, v143, s[0:1]
	global_load_ushort v167, v143, s[0:1] offset:32
	global_load_ushort v168, v143, s[0:1] offset:256
	global_load_ushort v169, v143, s[0:1] offset:288
	s_add_u32 s0, s0, 0x2000
	s_addc_u32 s1, s1, 0
	s_waitcnt vmcnt(16)
	v_lshlrev_b32_e32 v180, 16, v180
	v_lshlrev_b32_e32 v181, 16, v181
	v_lshlrev_b32_e32 v182, 16, v182
	v_lshlrev_b32_e32 v183, 16, v183
	v_max_f32_e32 v180, 0xda24260, v180
	v_max_f32_e32 v181, 0xda24260, v181
	v_max_f32_e32 v182, 0xda24260, v182
	v_max_f32_e32 v183, 0xda24260, v183
	v_rcp_f32_e32 v180, v180
	v_rcp_f32_e32 v181, v181
	v_rcp_f32_e32 v182, v182
	v_rcp_f32_e32 v183, v183
	v_lshlrev_b32_e32 v176, 16, v176
	v_lshlrev_b32_e32 v177, 16, v177
	v_lshlrev_b32_e32 v178, 16, v178
	v_lshlrev_b32_e32 v179, 16, v179
	v_mul_f32_e32 v176, v180, v176
	v_mul_f32_e32 v177, v181, v177
	v_mul_f32_e32 v178, v182, v178
	v_mul_f32_e32 v179, v183, v179
	v_mul_f32_e32 v50, v50, v176
	v_mul_f32_e32 v46, v46, v177
	v_mul_f32_e32 v42, v42, v178
	v_mul_f32_e32 v38, v38, v179
	v_lshlrev_b32_e32 v188, 16, v188
	v_lshlrev_b32_e32 v189, 16, v189
	v_lshlrev_b32_e32 v190, 16, v190
	v_lshlrev_b32_e32 v191, 16, v191
	v_max_f32_e32 v188, 0xda24260, v188
	v_max_f32_e32 v189, 0xda24260, v189
	v_max_f32_e32 v190, 0xda24260, v190
	v_max_f32_e32 v191, 0xda24260, v191
	v_rcp_f32_e32 v188, v188
	v_rcp_f32_e32 v189, v189
	v_rcp_f32_e32 v190, v190
	v_rcp_f32_e32 v191, v191
	v_lshlrev_b32_e32 v184, 16, v184
	v_lshlrev_b32_e32 v185, 16, v185
	v_lshlrev_b32_e32 v186, 16, v186
	v_lshlrev_b32_e32 v187, 16, v187
	v_mul_f32_e32 v184, v188, v184
	v_mul_f32_e32 v185, v189, v185
	v_mul_f32_e32 v186, v190, v186
	v_mul_f32_e32 v187, v191, v187
	v_mul_f32_e32 v51, v51, v184
	v_mul_f32_e32 v47, v47, v185
	v_mul_f32_e32 v43, v43, v186
	v_mul_f32_e32 v39, v39, v187
	global_load_ushort v176, v141, s[0:1]
	global_load_ushort v177, v141, s[0:1] offset:32
	global_load_ushort v178, v141, s[0:1] offset:256
	global_load_ushort v179, v141, s[0:1] offset:288
	global_load_ushort v180, v143, s[0:1]
	global_load_ushort v181, v143, s[0:1] offset:32
	global_load_ushort v182, v143, s[0:1] offset:256
	global_load_ushort v183, v143, s[0:1] offset:288
	s_add_u32 s0, s0, 0x2000
	s_addc_u32 s1, s1, 0
	global_load_ushort v184, v141, s[0:1]
	global_load_ushort v185, v141, s[0:1] offset:32
	global_load_ushort v186, v141, s[0:1] offset:256
	global_load_ushort v187, v141, s[0:1] offset:288
	global_load_ushort v188, v143, s[0:1]
	global_load_ushort v189, v143, s[0:1] offset:32
	global_load_ushort v190, v143, s[0:1] offset:256
	global_load_ushort v191, v143, s[0:1] offset:288
	s_add_u32 s0, s0, 0x1a000
	s_addc_u32 s1, s1, 0
	s_waitcnt vmcnt(16)
;     static __device__ __forceinline__ pg8::f32x4 up4(pg8::u32x2 a) { return (pg8::f32x4){__uint_as_float(a.x << 16), __uint_as_float(a.x & 0xffff0000u), __uint_as_float(a.y << 16), __uint_as_float(a.y & 0xffff0000u)}; }
;     __device__ __forceinline__ void mid(pg8::f32x4 (&acc)[2][2][4][2], const pg8::Unit& u, int wr, int wc, int fr, int fq) const {
;         int row0 = u.pm * 256 + wr * 64 + fr, col0 = u.pn * 256 + wc * 32 + 4 * fq;
;         asm volatile("" : "+v"(row0), "+v"(col0));
; #pragma unroll
;         for (int ai = 0; ai < 2; ++ai)
; #pragma unroll
;             for (int m = 0; m < 4; ++m) { const bf16* ap = AM + (size_t)(row0 + ai * 128 + m * 16) * 4096 + col0;
; #pragma unroll
;                 for (int bj = 0; bj < 2; ++bj)
; #pragma unroll
;                     for (int n = 0; n < 2; ++n) { const int c = bj * 128 + n * 16;
;                         const pg8::f32x4 a0 = up4(*(const pg8::u32x2*)(ap + c)), a1 = up4(*(const pg8::u32x2*)(ap + 2048 + c));
;                         pg8::f32x4 r; r[0] = a0[0] * __builtin_amdgcn_rcpf(fmaxf(a1[0], 1e-30f)); r[1] = a0[1] * __builtin_amdgcn_rcpf(fmaxf(a1[1], 1e-30f)); r[2] = a0[2] * __builtin_amdgcn_rcpf(fmaxf(a1[2], 1e-30f)); r[3] = a0[3] * __builtin_amdgcn_rcpf(fmaxf(a1[3], 1e-30f));
;                         acc[ai][bj][m][n] = acc[ai][bj][m][n] * r; }
;                 asm volatile("" ::: "memory"); }
	v_lshlrev_b32_e32 v158, 16, v158
	v_lshlrev_b32_e32 v159, 16, v159
	v_lshlrev_b32_e32 v160, 16, v160
	v_lshlrev_b32_e32 v161, 16, v161
	v_max_f32_e32 v158, 0xda24260, v158
	v_max_f32_e32 v159, 0xda24260, v159
	v_max_f32_e32 v160, 0xda24260, v160
	v_max_f32_e32 v161, 0xda24260, v161
	v_rcp_f32_e32 v158, v158
	v_rcp_f32_e32 v159, v159
	v_rcp_f32_e32 v160, v160
	v_rcp_f32_e32 v161, v161
	v_lshlrev_b32_e32 v148, 16, v148
	v_lshlrev_b32_e32 v149, 16, v149
	v_lshlrev_b32_e32 v150, 16, v150
	v_lshlrev_b32_e32 v151, 16, v151
	v_mul_f32_e32 v148, v158, v148
	v_mul_f32_e32 v149, v159, v149
	v_mul_f32_e32 v150, v160, v150
	v_mul_f32_e32 v151, v161, v151
	v_mul_f32_e32 v32, v32, v148
	v_mul_f32_e32 v28, v28, v149
	v_mul_f32_e32 v24, v24, v150
	v_mul_f32_e32 v20, v20, v151
	v_lshlrev_b32_e32 v166, 16, v166
	v_lshlrev_b32_e32 v167, 16, v167
	v_lshlrev_b32_e32 v168, 16, v168
	v_lshlrev_b32_e32 v169, 16, v169
	v_max_f32_e32 v166, 0xda24260, v166
	v_max_f32_e32 v167, 0xda24260, v167
	v_max_f32_e32 v168, 0xda24260, v168
	v_max_f32_e32 v169, 0xda24260, v169
	v_rcp_f32_e32 v166, v166
	v_rcp_f32_e32 v167, v167
	v_rcp_f32_e32 v168, v168
	v_rcp_f32_e32 v169, v169
	v_lshlrev_b32_e32 v162, 16, v162
	v_lshlrev_b32_e32 v163, 16, v163
	v_lshlrev_b32_e32 v164, 16, v164
	v_lshlrev_b32_e32 v165, 16, v165
	v_mul_f32_e32 v162, v166, v162
	v_mul_f32_e32 v163, v167, v163
	v_mul_f32_e32 v164, v168, v164
	v_mul_f32_e32 v165, v169, v165
	v_mul_f32_e32 v33, v33, v162
	v_mul_f32_e32 v29, v29, v163
	v_mul_f32_e32 v25, v25, v164
	v_mul_f32_e32 v21, v21, v165
	global_load_ushort v148, v141, s[0:1]
	global_load_ushort v149, v141, s[0:1] offset:32
	global_load_ushort v150, v141, s[0:1] offset:256
	global_load_ushort v151, v141, s[0:1] offset:288
	global_load_ushort v158, v143, s[0:1]
	global_load_ushort v159, v143, s[0:1] offset:32
	global_load_ushort v160, v143, s[0:1] offset:256
	global_load_ushort v161, v143, s[0:1] offset:288
	s_add_u32 s0, s0, 0x2000
	s_addc_u32 s1, s1, 0
	global_load_ushort v162, v141, s[0:1]
	global_load_ushort v163, v141, s[0:1] offset:32
	global_load_ushort v164, v141, s[0:1] offset:256
	global_load_ushort v165, v141, s[0:1] offset:288
	global_load_ushort v166, v143, s[0:1]
	global_load_ushort v167, v143, s[0:1] offset:32
	global_load_ushort v168, v143, s[0:1] offset:256
	global_load_ushort v169, v143, s[0:1] offset:288
	s_add_u32 s0, s0, 0x2000
	s_addc_u32 s1, s1, 0
	s_waitcnt vmcnt(16)
	v_lshlrev_b32_e32 v180, 16, v180
	v_lshlrev_b32_e32 v181, 16, v181
	v_lshlrev_b32_e32 v182, 16, v182
	v_lshlrev_b32_e32 v183, 16, v183
	v_max_f32_e32 v180, 0xda24260, v180
	v_max_f32_e32 v181, 0xda24260, v181
	v_max_f32_e32 v182, 0xda24260, v182
	v_max_f32_e32 v183, 0xda24260, v183
	v_rcp_f32_e32 v180, v180
	v_rcp_f32_e32 v181, v181
	v_rcp_f32_e32 v182, v182
	v_rcp_f32_e32 v183, v183
	v_lshlrev_b32_e32 v176, 16, v176
	v_lshlrev_b32_e32 v177, 16, v177
	v_lshlrev_b32_e32 v178, 16, v178
	v_lshlrev_b32_e32 v179, 16, v179
	v_mul_f32_e32 v176, v180, v176
	v_mul_f32_e32 v177, v181, v177
	v_mul_f32_e32 v178, v182, v178
	v_mul_f32_e32 v179, v183, v179
	v_mul_f32_e32 v34, v34, v176
	v_mul_f32_e32 v30, v30, v177
	v_mul_f32_e32 v26, v26, v178
	v_mul_f32_e32 v22, v22, v179
	v_lshlrev_b32_e32 v188, 16, v188
	v_lshlrev_b32_e32 v189, 16, v189
	v_lshlrev_b32_e32 v190, 16, v190
	v_lshlrev_b32_e32 v191, 16, v191
	v_max_f32_e32 v188, 0xda24260, v188
	v_max_f32_e32 v189, 0xda24260, v189
	v_max_f32_e32 v190, 0xda24260, v190
	v_max_f32_e32 v191, 0xda24260, v191
	v_rcp_f32_e32 v188, v188
	v_rcp_f32_e32 v189, v189
	v_rcp_f32_e32 v190, v190
	v_rcp_f32_e32 v191, v191
	v_lshlrev_b32_e32 v184, 16, v184
	v_lshlrev_b32_e32 v185, 16, v185
	v_lshlrev_b32_e32 v186, 16, v186
	v_lshlrev_b32_e32 v187, 16, v187
	v_mul_f32_e32 v184, v188, v184
	v_mul_f32_e32 v185, v189, v185
	v_mul_f32_e32 v186, v190, v186
	v_mul_f32_e32 v187, v191, v187
	v_mul_f32_e32 v35, v35, v184
	v_mul_f32_e32 v31, v31, v185
	v_mul_f32_e32 v27, v27, v186
	v_mul_f32_e32 v23, v23, v187
	global_load_ushort v176, v141, s[0:1]
	global_load_ushort v177, v141, s[0:1] offset:32
	global_load_ushort v178, v141, s[0:1] offset:256
	global_load_ushort v179, v141, s[0:1] offset:288
	global_load_ushort v180, v143, s[0:1]
	global_load_ushort v181, v143, s[0:1] offset:32
	global_load_ushort v182, v143, s[0:1] offset:256
	global_load_ushort v183, v143, s[0:1] offset:288
	s_add_u32 s0, s0, 0x2000
	s_addc_u32 s1, s1, 0
	global_load_ushort v184, v141, s[0:1]
	global_load_ushort v185, v141, s[0:1] offset:32
	global_load_ushort v186, v141, s[0:1] offset:256
	global_load_ushort v187, v141, s[0:1] offset:288
	global_load_ushort v188, v143, s[0:1]
	global_load_ushort v189, v143, s[0:1] offset:32
	global_load_ushort v190, v143, s[0:1] offset:256
	global_load_ushort v191, v143, s[0:1] offset:288
	s_waitcnt vmcnt(16)
;     static __device__ __forceinline__ pg8::f32x4 up4(pg8::u32x2 a) { return (pg8::f32x4){__uint_as_float(a.x << 16), __uint_as_float(a.x & 0xffff0000u), __uint_as_float(a.y << 16), __uint_as_float(a.y & 0xffff0000u)}; }
;     __device__ __forceinline__ void mid(pg8::f32x4 (&acc)[2][2][4][2], const pg8::Unit& u, int wr, int wc, int fr, int fq) const {
;         int row0 = u.pm * 256 + wr * 64 + fr, col0 = u.pn * 256 + wc * 32 + 4 * fq;
;         asm volatile("" : "+v"(row0), "+v"(col0));
; #pragma unroll
;         for (int ai = 0; ai < 2; ++ai)
; #pragma unroll
;             for (int m = 0; m < 4; ++m) { const bf16* ap = AM + (size_t)(row0 + ai * 128 + m * 16) * 4096 + col0;
; #pragma unroll
;                 for (int bj = 0; bj < 2; ++bj)
; #pragma unroll
;                     for (int n = 0; n < 2; ++n) { const int c = bj * 128 + n * 16;
;                         const pg8::f32x4 a0 = up4(*(const pg8::u32x2*)(ap + c)), a1 = up4(*(const pg8::u32x2*)(ap + 2048 + c));
;                         pg8::f32x4 r; r[0] = a0[0] * __builtin_amdgcn_rcpf(fmaxf(a1[0], 1e-30f)); r[1] = a0[1] * __builtin_amdgcn_rcpf(fmaxf(a1[1], 1e-30f)); r[2] = a0[2] * __builtin_amdgcn_rcpf(fmaxf(a1[2], 1e-30f)); r[3] = a0[3] * __builtin_amdgcn_rcpf(fmaxf(a1[3], 1e-30f));
;                         acc[ai][bj][m][n] = acc[ai][bj][m][n] * r; }
;                 asm volatile("" ::: "memory"); }
	v_lshlrev_b32_e32 v158, 16, v158
	v_lshlrev_b32_e32 v159, 16, v159
	v_lshlrev_b32_e32 v160, 16, v160
	v_lshlrev_b32_e32 v161, 16, v161
	v_max_f32_e32 v158, 0xda24260, v158
	v_max_f32_e32 v159, 0xda24260, v159
	v_max_f32_e32 v160, 0xda24260, v160
	v_max_f32_e32 v161, 0xda24260, v161
	v_rcp_f32_e32 v158, v158
	v_rcp_f32_e32 v159, v159
	v_rcp_f32_e32 v160, v160
	v_rcp_f32_e32 v161, v161
	v_lshlrev_b32_e32 v148, 16, v148
	v_lshlrev_b32_e32 v149, 16, v149
	v_lshlrev_b32_e32 v150, 16, v150
	v_lshlrev_b32_e32 v151, 16, v151
	v_mul_f32_e32 v148, v158, v148
	v_mul_f32_e32 v149, v159, v149
	v_mul_f32_e32 v150, v160, v150
	v_mul_f32_e32 v151, v161, v151
	v_mul_f32_e32 v16, v16, v148
	v_mul_f32_e32 v12, v12, v149
	v_mul_f32_e32 v8, v8, v150
	v_mul_f32_e32 v4, v4, v151
	v_lshlrev_b32_e32 v166, 16, v166
	v_lshlrev_b32_e32 v167, 16, v167
	v_lshlrev_b32_e32 v168, 16, v168
	v_lshlrev_b32_e32 v169, 16, v169
	v_max_f32_e32 v166, 0xda24260, v166
	v_max_f32_e32 v167, 0xda24260, v167
	v_max_f32_e32 v168, 0xda24260, v168
	v_max_f32_e32 v169, 0xda24260, v169
	v_rcp_f32_e32 v166, v166
	v_rcp_f32_e32 v167, v167
	v_rcp_f32_e32 v168, v168
	v_rcp_f32_e32 v169, v169
	v_lshlrev_b32_e32 v162, 16, v162
	v_lshlrev_b32_e32 v163, 16, v163
	v_lshlrev_b32_e32 v164, 16, v164
	v_lshlrev_b32_e32 v165, 16, v165
	v_mul_f32_e32 v162, v166, v162
	v_mul_f32_e32 v163, v167, v163
	v_mul_f32_e32 v164, v168, v164
	v_mul_f32_e32 v165, v169, v165
	v_mul_f32_e32 v17, v17, v162
	v_mul_f32_e32 v13, v13, v163
	v_mul_f32_e32 v9, v9, v164
	v_mul_f32_e32 v5, v5, v165
	s_waitcnt vmcnt(0)
	v_lshlrev_b32_e32 v180, 16, v180
	v_lshlrev_b32_e32 v181, 16, v181
	v_lshlrev_b32_e32 v182, 16, v182
	v_lshlrev_b32_e32 v183, 16, v183
	v_max_f32_e32 v180, 0xda24260, v180
	v_max_f32_e32 v181, 0xda24260, v181
	v_max_f32_e32 v182, 0xda24260, v182
	v_max_f32_e32 v183, 0xda24260, v183
	v_rcp_f32_e32 v180, v180
	v_rcp_f32_e32 v181, v181
	v_rcp_f32_e32 v182, v182
	v_rcp_f32_e32 v183, v183
	v_lshlrev_b32_e32 v176, 16, v176
	v_lshlrev_b32_e32 v177, 16, v177
	v_lshlrev_b32_e32 v178, 16, v178
	v_lshlrev_b32_e32 v179, 16, v179
	v_mul_f32_e32 v176, v180, v176
	v_mul_f32_e32 v177, v181, v177
	v_mul_f32_e32 v178, v182, v178
	v_mul_f32_e32 v179, v183, v179
	v_mul_f32_e32 v18, v18, v176
	v_mul_f32_e32 v14, v14, v177
	v_mul_f32_e32 v10, v10, v178
	v_mul_f32_e32 v6, v6, v179
	v_lshlrev_b32_e32 v188, 16, v188
	v_lshlrev_b32_e32 v189, 16, v189
	v_lshlrev_b32_e32 v190, 16, v190
	v_lshlrev_b32_e32 v191, 16, v191
	v_max_f32_e32 v188, 0xda24260, v188
	v_max_f32_e32 v189, 0xda24260, v189
	v_max_f32_e32 v190, 0xda24260, v190
	v_max_f32_e32 v191, 0xda24260, v191
	v_rcp_f32_e32 v188, v188
	v_rcp_f32_e32 v189, v189
	v_rcp_f32_e32 v190, v190
	v_rcp_f32_e32 v191, v191
	v_lshlrev_b32_e32 v184, 16, v184
	v_lshlrev_b32_e32 v185, 16, v185
	v_lshlrev_b32_e32 v186, 16, v186
	v_lshlrev_b32_e32 v187, 16, v187
	v_mul_f32_e32 v184, v188, v184
	v_mul_f32_e32 v185, v189, v185
	v_mul_f32_e32 v186, v190, v186
	v_mul_f32_e32 v187, v191, v187
	v_mul_f32_e32 v19, v19, v184
	v_mul_f32_e32 v15, v15, v185
	v_mul_f32_e32 v11, v11, v186
	v_mul_f32_e32 v7, v7, v187
	s_branch .LBB0_1601

; __device__ __forceinline__ unsigned cvt_pk_bf16(float lo, float hi) { const pk_f2_t v = {lo, hi}; return __builtin_bit_cast(unsigned, __builtin_convertvector(v, pk_bf2_t)); }
;     static __device__ __forceinline__ pg8::f32x4 up4(pg8::u32x2 a) { return (pg8::f32x4){__uint_as_float(a.x << 16), __uint_as_float(a.x & 0xffff0000u), __uint_as_float(a.y << 16), __uint_as_float(a.y & 0xffff0000u)}; }
;     __device__ __forceinline__ void operator()(const pg8::f32x4 (&acc)[2][2][4][2], const pg8::Unit& u, int wr, int wc, int fr, int fq) const {
;         const int row0 = u.pm * 256 + wr * 64 + fr, col0 = u.pn * 256 + wc * 32 + 4 * fq;
; #pragma unroll
;         for (int ai = 0; ai < 2; ++ai)
; #pragma unroll
;             for (int m = 0; m < 4; ++m) { const size_t r = (size_t)(row0 + ai * 128 + m * 16);
; #pragma unroll
;                 for (int bj = 0; bj < 2; ++bj)
; #pragma unroll
;                     for (int n = 0; n < 2; ++n) { const int c = col0 + bj * 128 + n * 16;
;                         const pg8::f32x4 y = up4(*(const pg8::u32x2*)(AM + r * 4096 + 2048 + c)) * acc[ai][bj][m][n];
;                         pg8::u32x2 w; w.x = pg8::cvt_pk_bf16(y[0], y[1]); w.y = pg8::cvt_pk_bf16(y[2], y[3]);
;                         *(pg8::u32x2*)(Y + r * D + c) = w; }
;                 asm volatile("" ::: "memory"); }
.LBB0_1606:
	v_and_b32_e32 v143, -16, v140
	v_and_b32_e32 v0, 12, v142
	v_or_b32_e32 v143, v143, v0
	v_and_b32_e32 v0, -32, v142
	v_and_or_b32 v0, v140, 15, v0
	v_lshlrev_b32_e32 v0, 1, v0
	v_lshl_add_u32 v2, v143, 12, v0
	v_lshl_add_u32 v143, v143, 13, v0
	v_add_u32_e32 v143, 0x1000, v143
	s_mov_b64 s[0:1], s[14:15]
	s_mov_b64 s[100:101], s[42:43]
	global_load_ushort v148, v143, s[0:1]
	global_load_ushort v149, v143, s[0:1] offset:32
	global_load_ushort v150, v143, s[0:1] offset:256
	global_load_ushort v151, v143, s[0:1] offset:288
	s_add_u32 s0, s0, 0x2000
	s_addc_u32 s1, s1, 0
	global_load_ushort v158, v143, s[0:1]
	global_load_ushort v159, v143, s[0:1] offset:32
	global_load_ushort v160, v143, s[0:1] offset:256
	global_load_ushort v161, v143, s[0:1] offset:288
	s_add_u32 s0, s0, 0x2000
	s_addc_u32 s1, s1, 0
	global_load_ushort v162, v143, s[0:1]
	global_load_ushort v163, v143, s[0:1] offset:32
	global_load_ushort v164, v143, s[0:1] offset:256
	global_load_ushort v165, v143, s[0:1] offset:288
	s_add_u32 s0, s0, 0x2000
	s_addc_u32 s1, s1, 0
	global_load_ushort v166, v143, s[0:1]
	global_load_ushort v167, v143, s[0:1] offset:32
	global_load_ushort v168, v143, s[0:1] offset:256
	global_load_ushort v169, v143, s[0:1] offset:288
	s_add_u32 s0, s0, 0x1a000
	s_addc_u32 s1, s1, 0
	global_load_ushort v176, v143, s[0:1]
	global_load_ushort v177, v143, s[0:1] offset:32
	global_load_ushort v178, v143, s[0:1] offset:256
	global_load_ushort v179, v143, s[0:1] offset:288
	s_add_u32 s0, s0, 0x2000
	s_addc_u32 s1, s1, 0
	global_load_ushort v180, v143, s[0:1]
	global_load_ushort v181, v143, s[0:1] offset:32
	global_load_ushort v182, v143, s[0:1] offset:256
	global_load_ushort v183, v143, s[0:1] offset:288
	s_add_u32 s0, s0, 0x2000
	s_addc_u32 s1, s1, 0
	global_load_ushort v184, v143, s[0:1]
	global_load_ushort v185, v143, s[0:1] offset:32
	global_load_ushort v186, v143, s[0:1] offset:256
	global_load_ushort v187, v143, s[0:1] offset:288
	s_add_u32 s0, s0, 0x2000
	s_addc_u32 s1, s1, 0
	global_load_ushort v188, v143, s[0:1]
	global_load_ushort v189, v143, s[0:1] offset:32
	global_load_ushort v190, v143, s[0:1] offset:256
	global_load_ushort v191, v143, s[0:1] offset:288
	s_add_u32 s0, s0, 0x1a000
	s_addc_u32 s1, s1, 0
	s_waitcnt vmcnt(16)
	v_lshlrev_b32_e32 v148, 16, v148
	v_lshlrev_b32_e32 v149, 16, v149
	v_lshlrev_b32_e32 v150, 16, v150
	v_lshlrev_b32_e32 v151, 16, v151
	v_mul_f32_e32 v128, v128, v148
	v_mul_f32_e32 v124, v124, v149
	v_mul_f32_e32 v120, v120, v150
	v_mul_f32_e32 v116, v116, v151
	v_cvt_pk_bf16_f32 v128, v128, v128
	v_cvt_pk_bf16_f32 v124, v124, v124
	v_cvt_pk_bf16_f32 v120, v120, v120
	v_cvt_pk_bf16_f32 v116, v116, v116
	global_store_short v2, v128, s[100:101]
	global_store_short v2, v124, s[100:101] offset:32
	global_store_short v2, v120, s[100:101] offset:256
	global_store_short v2, v116, s[100:101] offset:288
	s_add_u32 s100, s100, 0x1000
	s_addc_u32 s101, s101, 0
	v_lshlrev_b32_e32 v158, 16, v158
	v_lshlrev_b32_e32 v159, 16, v159
	v_lshlrev_b32_e32 v160, 16, v160
	v_lshlrev_b32_e32 v161, 16, v161
	v_mul_f32_e32 v129, v129, v158
	v_mul_f32_e32 v125, v125, v159
	v_mul_f32_e32 v121, v121, v160
	v_mul_f32_e32 v117, v117, v161
	v_cvt_pk_bf16_f32 v129, v129, v129
	v_cvt_pk_bf16_f32 v125, v125, v125
	v_cvt_pk_bf16_f32 v121, v121, v121
	v_cvt_pk_bf16_f32 v117, v117, v117
	global_store_short v2, v129, s[100:101]
	global_store_short v2, v125, s[100:101] offset:32
	global_store_short v2, v121, s[100:101] offset:256
	global_store_short v2, v117, s[100:101] offset:288
	s_add_u32 s100, s100, 0x1000
	s_addc_u32 s101, s101, 0
	v_lshlrev_b32_e32 v162, 16, v162
	v_lshlrev_b32_e32 v163, 16, v163
	v_lshlrev_b32_e32 v164, 16, v164
	v_lshlrev_b32_e32 v165, 16, v165
	v_mul_f32_e32 v130, v130, v162
	v_mul_f32_e32 v126, v126, v163
	v_mul_f32_e32 v122, v122, v164
	v_mul_f32_e32 v118, v118, v165
	v_cvt_pk_bf16_f32 v130, v130, v130
	v_cvt_pk_bf16_f32 v126, v126, v126
	v_cvt_pk_bf16_f32 v122, v122, v122
	v_cvt_pk_bf16_f32 v118, v118, v118
	global_store_short v2, v130, s[100:101]
	global_store_short v2, v126, s[100:101] offset:32
	global_store_short v2, v122, s[100:101] offset:256
	global_store_short v2, v118, s[100:101] offset:288
	s_add_u32 s100, s100, 0x1000
	s_addc_u32 s101, s101, 0
	v_lshlrev_b32_e32 v166, 16, v166
	v_lshlrev_b32_e32 v167, 16, v167
	v_lshlrev_b32_e32 v168, 16, v168
	v_lshlrev_b32_e32 v169, 16, v169
	v_mul_f32_e32 v131, v131, v166
	v_mul_f32_e32 v127, v127, v167
	v_mul_f32_e32 v123, v123, v168
	v_mul_f32_e32 v119, v119, v169
	v_cvt_pk_bf16_f32 v131, v131, v131
	v_cvt_pk_bf16_f32 v127, v127, v127
	v_cvt_pk_bf16_f32 v123, v123, v123
	v_cvt_pk_bf16_f32 v119, v119, v119
	global_store_short v2, v131, s[100:101]
	global_store_short v2, v127, s[100:101] offset:32
	global_store_short v2, v123, s[100:101] offset:256
	global_store_short v2, v119, s[100:101] offset:288
	s_add_u32 s100, s100, 0xd000
	s_addc_u32 s101, s101, 0
	global_load_ushort v148, v143, s[0:1]
	global_load_ushort v149, v143, s[0:1] offset:32
	global_load_ushort v150, v143, s[0:1] offset:256
	global_load_ushort v151, v143, s[0:1] offset:288
	s_add_u32 s0, s0, 0x2000
	s_addc_u32 s1, s1, 0
	global_load_ushort v158, v143, s[0:1]
	global_load_ushort v159, v143, s[0:1] offset:32
	global_load_ushort v160, v143, s[0:1] offset:256
	global_load_ushort v161, v143, s[0:1] offset:288
	s_add_u32 s0, s0, 0x2000
	s_addc_u32 s1, s1, 0
	global_load_ushort v162, v143, s[0:1]
	global_load_ushort v163, v143, s[0:1] offset:32
	global_load_ushort v164, v143, s[0:1] offset:256
	global_load_ushort v165, v143, s[0:1] offset:288
	s_add_u32 s0, s0, 0x2000
	s_addc_u32 s1, s1, 0
	global_load_ushort v166, v143, s[0:1]
	global_load_ushort v167, v143, s[0:1] offset:32
	global_load_ushort v168, v143, s[0:1] offset:256
	global_load_ushort v169, v143, s[0:1] offset:288
	s_add_u32 s0, s0, 0x1a000
	s_addc_u32 s1, s1, 0
	s_waitcnt vmcnt(32)
; __device__ __forceinline__ unsigned cvt_pk_bf16(float lo, float hi) { const pk_f2_t v = {lo, hi}; return __builtin_bit_cast(unsigned, __builtin_convertvector(v, pk_bf2_t)); }
;     static __device__ __forceinline__ pg8::f32x4 up4(pg8::u32x2 a) { return (pg8::f32x4){__uint_as_float(a.x << 16), __uint_as_float(a.x & 0xffff0000u), __uint_as_float(a.y << 16), __uint_as_float(a.y & 0xffff0000u)}; }
;     __device__ __forceinline__ void operator()(const pg8::f32x4 (&acc)[2][2][4][2], const pg8::Unit& u, int wr, int wc, int fr, int fq) const {
;         const int row0 = u.pm * 256 + wr * 64 + fr, col0 = u.pn * 256 + wc * 32 + 4 * fq;
; #pragma unroll
;         for (int ai = 0; ai < 2; ++ai)
; #pragma unroll
;             for (int m = 0; m < 4; ++m) { const size_t r = (size_t)(row0 + ai * 128 + m * 16);
; #pragma unroll
;                 for (int bj = 0; bj < 2; ++bj)
; #pragma unroll
;                     for (int n = 0; n < 2; ++n) { const int c = col0 + bj * 128 + n * 16;
;                         const pg8::f32x4 y = up4(*(const pg8::u32x2*)(AM + r * 4096 + 2048 + c)) * acc[ai][bj][m][n];
;                         pg8::u32x2 w; w.x = pg8::cvt_pk_bf16(y[0], y[1]); w.y = pg8::cvt_pk_bf16(y[2], y[3]);
;                         *(pg8::u32x2*)(Y + r * D + c) = w; }
;                 asm volatile("" ::: "memory"); }
	v_lshlrev_b32_e32 v176, 16, v176
	v_lshlrev_b32_e32 v177, 16, v177
	v_lshlrev_b32_e32 v178, 16, v178
	v_lshlrev_b32_e32 v179, 16, v179
	v_mul_f32_e32 v112, v112, v176
	v_mul_f32_e32 v108, v108, v177
	v_mul_f32_e32 v104, v104, v178
	v_mul_f32_e32 v100, v100, v179
	v_cvt_pk_bf16_f32 v112, v112, v112
	v_cvt_pk_bf16_f32 v108, v108, v108
	v_cvt_pk_bf16_f32 v104, v104, v104
	v_cvt_pk_bf16_f32 v100, v100, v100
	global_store_short v2, v112, s[100:101]
	global_store_short v2, v108, s[100:101] offset:32
	global_store_short v2, v104, s[100:101] offset:256
	global_store_short v2, v100, s[100:101] offset:288
	s_add_u32 s100, s100, 0x1000
	s_addc_u32 s101, s101, 0
	v_lshlrev_b32_e32 v180, 16, v180
	v_lshlrev_b32_e32 v181, 16, v181
	v_lshlrev_b32_e32 v182, 16, v182
	v_lshlrev_b32_e32 v183, 16, v183
	v_mul_f32_e32 v113, v113, v180
	v_mul_f32_e32 v109, v109, v181
	v_mul_f32_e32 v105, v105, v182
	v_mul_f32_e32 v101, v101, v183
	v_cvt_pk_bf16_f32 v113, v113, v113
	v_cvt_pk_bf16_f32 v109, v109, v109
	v_cvt_pk_bf16_f32 v105, v105, v105
	v_cvt_pk_bf16_f32 v101, v101, v101
	global_store_short v2, v113, s[100:101]
	global_store_short v2, v109, s[100:101] offset:32
	global_store_short v2, v105, s[100:101] offset:256
	global_store_short v2, v101, s[100:101] offset:288
	s_add_u32 s100, s100, 0x1000
	s_addc_u32 s101, s101, 0
	v_lshlrev_b32_e32 v184, 16, v184
	v_lshlrev_b32_e32 v185, 16, v185
	v_lshlrev_b32_e32 v186, 16, v186
	v_lshlrev_b32_e32 v187, 16, v187
	v_mul_f32_e32 v114, v114, v184
	v_mul_f32_e32 v110, v110, v185
	v_mul_f32_e32 v106, v106, v186
	v_mul_f32_e32 v102, v102, v187
	v_cvt_pk_bf16_f32 v114, v114, v114
	v_cvt_pk_bf16_f32 v110, v110, v110
	v_cvt_pk_bf16_f32 v106, v106, v106
	v_cvt_pk_bf16_f32 v102, v102, v102
	global_store_short v2, v114, s[100:101]
	global_store_short v2, v110, s[100:101] offset:32
	global_store_short v2, v106, s[100:101] offset:256
	global_store_short v2, v102, s[100:101] offset:288
	s_add_u32 s100, s100, 0x1000
	s_addc_u32 s101, s101, 0
	v_lshlrev_b32_e32 v188, 16, v188
	v_lshlrev_b32_e32 v189, 16, v189
	v_lshlrev_b32_e32 v190, 16, v190
	v_lshlrev_b32_e32 v191, 16, v191
	v_mul_f32_e32 v115, v115, v188
	v_mul_f32_e32 v111, v111, v189
	v_mul_f32_e32 v107, v107, v190
	v_mul_f32_e32 v103, v103, v191
	v_cvt_pk_bf16_f32 v115, v115, v115
	v_cvt_pk_bf16_f32 v111, v111, v111
	v_cvt_pk_bf16_f32 v107, v107, v107
	v_cvt_pk_bf16_f32 v103, v103, v103
	global_store_short v2, v115, s[100:101]
	global_store_short v2, v111, s[100:101] offset:32
	global_store_short v2, v107, s[100:101] offset:256
	global_store_short v2, v103, s[100:101] offset:288
	s_add_u32 s100, s100, 0xd000
	s_addc_u32 s101, s101, 0
	global_load_ushort v176, v143, s[0:1]
	global_load_ushort v177, v143, s[0:1] offset:32
	global_load_ushort v178, v143, s[0:1] offset:256
	global_load_ushort v179, v143, s[0:1] offset:288
	s_add_u32 s0, s0, 0x2000
	s_addc_u32 s1, s1, 0
	global_load_ushort v180, v143, s[0:1]
	global_load_ushort v181, v143, s[0:1] offset:32
	global_load_ushort v182, v143, s[0:1] offset:256
	global_load_ushort v183, v143, s[0:1] offset:288
	s_add_u32 s0, s0, 0x2000
	s_addc_u32 s1, s1, 0
	global_load_ushort v184, v143, s[0:1]
	global_load_ushort v185, v143, s[0:1] offset:32
	global_load_ushort v186, v143, s[0:1] offset:256
	global_load_ushort v187, v143, s[0:1] offset:288
	s_add_u32 s0, s0, 0x2000
	s_addc_u32 s1, s1, 0
	global_load_ushort v188, v143, s[0:1]
	global_load_ushort v189, v143, s[0:1] offset:32
	global_load_ushort v190, v143, s[0:1] offset:256
	global_load_ushort v191, v143, s[0:1] offset:288
	s_add_u32 s0, s0, 0x9a000
	s_addc_u32 s1, s1, 0
	s_waitcnt vmcnt(32)
	v_lshlrev_b32_e32 v148, 16, v148
	v_lshlrev_b32_e32 v149, 16, v149
	v_lshlrev_b32_e32 v150, 16, v150
	v_lshlrev_b32_e32 v151, 16, v151
	v_mul_f32_e32 v96, v96, v148
	v_mul_f32_e32 v92, v92, v149
	v_mul_f32_e32 v88, v88, v150
	v_mul_f32_e32 v84, v84, v151
	v_cvt_pk_bf16_f32 v96, v96, v96
	v_cvt_pk_bf16_f32 v92, v92, v92
	v_cvt_pk_bf16_f32 v88, v88, v88
	v_cvt_pk_bf16_f32 v84, v84, v84
	global_store_short v2, v96, s[100:101]
	global_store_short v2, v92, s[100:101] offset:32
	global_store_short v2, v88, s[100:101] offset:256
	global_store_short v2, v84, s[100:101] offset:288
	s_add_u32 s100, s100, 0x1000
	s_addc_u32 s101, s101, 0
	v_lshlrev_b32_e32 v158, 16, v158
	v_lshlrev_b32_e32 v159, 16, v159
	v_lshlrev_b32_e32 v160, 16, v160
	v_lshlrev_b32_e32 v161, 16, v161
	v_mul_f32_e32 v97, v97, v158
	v_mul_f32_e32 v93, v93, v159
	v_mul_f32_e32 v89, v89, v160
	v_mul_f32_e32 v85, v85, v161
	v_cvt_pk_bf16_f32 v97, v97, v97
	v_cvt_pk_bf16_f32 v93, v93, v93
	v_cvt_pk_bf16_f32 v89, v89, v89
	v_cvt_pk_bf16_f32 v85, v85, v85
	global_store_short v2, v97, s[100:101]
	global_store_short v2, v93, s[100:101] offset:32
	global_store_short v2, v89, s[100:101] offset:256
	global_store_short v2, v85, s[100:101] offset:288
	s_add_u32 s100, s100, 0x1000
	s_addc_u32 s101, s101, 0
	v_lshlrev_b32_e32 v162, 16, v162
	v_lshlrev_b32_e32 v163, 16, v163
	v_lshlrev_b32_e32 v164, 16, v164
	v_lshlrev_b32_e32 v165, 16, v165
	v_mul_f32_e32 v98, v98, v162
	v_mul_f32_e32 v94, v94, v163
	v_mul_f32_e32 v90, v90, v164
	v_mul_f32_e32 v86, v86, v165
	v_cvt_pk_bf16_f32 v98, v98, v98
	v_cvt_pk_bf16_f32 v94, v94, v94
	v_cvt_pk_bf16_f32 v90, v90, v90
	v_cvt_pk_bf16_f32 v86, v86, v86
	global_store_short v2, v98, s[100:101]
	global_store_short v2, v94, s[100:101] offset:32
	global_store_short v2, v90, s[100:101] offset:256
	global_store_short v2, v86, s[100:101] offset:288
	s_add_u32 s100, s100, 0x1000
	s_addc_u32 s101, s101, 0
	v_lshlrev_b32_e32 v166, 16, v166
	v_lshlrev_b32_e32 v167, 16, v167
	v_lshlrev_b32_e32 v168, 16, v168
	v_lshlrev_b32_e32 v169, 16, v169
; __device__ __forceinline__ unsigned cvt_pk_bf16(float lo, float hi) { const pk_f2_t v = {lo, hi}; return __builtin_bit_cast(unsigned, __builtin_convertvector(v, pk_bf2_t)); }
;     static __device__ __forceinline__ pg8::f32x4 up4(pg8::u32x2 a) { return (pg8::f32x4){__uint_as_float(a.x << 16), __uint_as_float(a.x & 0xffff0000u), __uint_as_float(a.y << 16), __uint_as_float(a.y & 0xffff0000u)}; }
;     __device__ __forceinline__ void operator()(const pg8::f32x4 (&acc)[2][2][4][2], const pg8::Unit& u, int wr, int wc, int fr, int fq) const {
;         const int row0 = u.pm * 256 + wr * 64 + fr, col0 = u.pn * 256 + wc * 32 + 4 * fq;
; #pragma unroll
;         for (int ai = 0; ai < 2; ++ai)
; #pragma unroll
;             for (int m = 0; m < 4; ++m) { const size_t r = (size_t)(row0 + ai * 128 + m * 16);
; #pragma unroll
;                 for (int bj = 0; bj < 2; ++bj)
; #pragma unroll
;                     for (int n = 0; n < 2; ++n) { const int c = col0 + bj * 128 + n * 16;
;                         const pg8::f32x4 y = up4(*(const pg8::u32x2*)(AM + r * 4096 + 2048 + c)) * acc[ai][bj][m][n];
;                         pg8::u32x2 w; w.x = pg8::cvt_pk_bf16(y[0], y[1]); w.y = pg8::cvt_pk_bf16(y[2], y[3]);
;                         *(pg8::u32x2*)(Y + r * D + c) = w; }
;                 asm volatile("" ::: "memory"); }
	v_mul_f32_e32 v99, v99, v166
	v_mul_f32_e32 v95, v95, v167
	v_mul_f32_e32 v91, v91, v168
	v_mul_f32_e32 v87, v87, v169
	v_cvt_pk_bf16_f32 v99, v99, v99
	v_cvt_pk_bf16_f32 v95, v95, v95
	v_cvt_pk_bf16_f32 v91, v91, v91
	v_cvt_pk_bf16_f32 v87, v87, v87
	global_store_short v2, v99, s[100:101]
	global_store_short v2, v95, s[100:101] offset:32
	global_store_short v2, v91, s[100:101] offset:256
	global_store_short v2, v87, s[100:101] offset:288
	s_add_u32 s100, s100, 0xd000
	s_addc_u32 s101, s101, 0
	global_load_ushort v148, v143, s[0:1]
	global_load_ushort v149, v143, s[0:1] offset:32
	global_load_ushort v150, v143, s[0:1] offset:256
	global_load_ushort v151, v143, s[0:1] offset:288
	s_add_u32 s0, s0, 0x2000
	s_addc_u32 s1, s1, 0
	global_load_ushort v158, v143, s[0:1]
	global_load_ushort v159, v143, s[0:1] offset:32
	global_load_ushort v160, v143, s[0:1] offset:256
	global_load_ushort v161, v143, s[0:1] offset:288
	s_add_u32 s0, s0, 0x2000
	s_addc_u32 s1, s1, 0
	global_load_ushort v162, v143, s[0:1]
	global_load_ushort v163, v143, s[0:1] offset:32
	global_load_ushort v164, v143, s[0:1] offset:256
	global_load_ushort v165, v143, s[0:1] offset:288
	s_add_u32 s0, s0, 0x2000
	s_addc_u32 s1, s1, 0
	global_load_ushort v166, v143, s[0:1]
	global_load_ushort v167, v143, s[0:1] offset:32
	global_load_ushort v168, v143, s[0:1] offset:256
	global_load_ushort v169, v143, s[0:1] offset:288
	s_add_u32 s0, s0, 0x1a000
	s_addc_u32 s1, s1, 0
	s_waitcnt vmcnt(32)
	v_lshlrev_b32_e32 v176, 16, v176
	v_lshlrev_b32_e32 v177, 16, v177
	v_lshlrev_b32_e32 v178, 16, v178
	v_lshlrev_b32_e32 v179, 16, v179
	v_mul_f32_e32 v80, v80, v176
	v_mul_f32_e32 v76, v76, v177
	v_mul_f32_e32 v72, v72, v178
	v_mul_f32_e32 v68, v68, v179
	v_cvt_pk_bf16_f32 v80, v80, v80
	v_cvt_pk_bf16_f32 v76, v76, v76
	v_cvt_pk_bf16_f32 v72, v72, v72
	v_cvt_pk_bf16_f32 v68, v68, v68
	global_store_short v2, v80, s[100:101]
	global_store_short v2, v76, s[100:101] offset:32
	global_store_short v2, v72, s[100:101] offset:256
	global_store_short v2, v68, s[100:101] offset:288
	s_add_u32 s100, s100, 0x1000
	s_addc_u32 s101, s101, 0
	v_lshlrev_b32_e32 v180, 16, v180
	v_lshlrev_b32_e32 v181, 16, v181
	v_lshlrev_b32_e32 v182, 16, v182
	v_lshlrev_b32_e32 v183, 16, v183
	v_mul_f32_e32 v81, v81, v180
	v_mul_f32_e32 v77, v77, v181
	v_mul_f32_e32 v73, v73, v182
	v_mul_f32_e32 v69, v69, v183
	v_cvt_pk_bf16_f32 v81, v81, v81
	v_cvt_pk_bf16_f32 v77, v77, v77
	v_cvt_pk_bf16_f32 v73, v73, v73
	v_cvt_pk_bf16_f32 v69, v69, v69
	global_store_short v2, v81, s[100:101]
	global_store_short v2, v77, s[100:101] offset:32
	global_store_short v2, v73, s[100:101] offset:256
	global_store_short v2, v69, s[100:101] offset:288
	s_add_u32 s100, s100, 0x1000
	s_addc_u32 s101, s101, 0
	v_lshlrev_b32_e32 v184, 16, v184
	v_lshlrev_b32_e32 v185, 16, v185
	v_lshlrev_b32_e32 v186, 16, v186
	v_lshlrev_b32_e32 v187, 16, v187
	v_mul_f32_e32 v82, v82, v184
	v_mul_f32_e32 v78, v78, v185
	v_mul_f32_e32 v74, v74, v186
	v_mul_f32_e32 v70, v70, v187
	v_cvt_pk_bf16_f32 v82, v82, v82
	v_cvt_pk_bf16_f32 v78, v78, v78
	v_cvt_pk_bf16_f32 v74, v74, v74
	v_cvt_pk_bf16_f32 v70, v70, v70
	global_store_short v2, v82, s[100:101]
	global_store_short v2, v78, s[100:101] offset:32
	global_store_short v2, v74, s[100:101] offset:256
	global_store_short v2, v70, s[100:101] offset:288
	s_add_u32 s100, s100, 0x1000
	s_addc_u32 s101, s101, 0
	v_lshlrev_b32_e32 v188, 16, v188
	v_lshlrev_b32_e32 v189, 16, v189
	v_lshlrev_b32_e32 v190, 16, v190
	v_lshlrev_b32_e32 v191, 16, v191
	v_mul_f32_e32 v83, v83, v188
	v_mul_f32_e32 v79, v79, v189
	v_mul_f32_e32 v75, v75, v190
	v_mul_f32_e32 v71, v71, v191
	v_cvt_pk_bf16_f32 v83, v83, v83
	v_cvt_pk_bf16_f32 v79, v79, v79
	v_cvt_pk_bf16_f32 v75, v75, v75
	v_cvt_pk_bf16_f32 v71, v71, v71
	global_store_short v2, v83, s[100:101]
	global_store_short v2, v79, s[100:101] offset:32
	global_store_short v2, v75, s[100:101] offset:256
	global_store_short v2, v71, s[100:101] offset:288
	s_add_u32 s100, s100, 0x4d000
	s_addc_u32 s101, s101, 0
	global_load_ushort v176, v143, s[0:1]
	global_load_ushort v177, v143, s[0:1] offset:32
	global_load_ushort v178, v143, s[0:1] offset:256
	global_load_ushort v179, v143, s[0:1] offset:288
	s_add_u32 s0, s0, 0x2000
	s_addc_u32 s1, s1, 0
	global_load_ushort v180, v143, s[0:1]
	global_load_ushort v181, v143, s[0:1] offset:32
	global_load_ushort v182, v143, s[0:1] offset:256
	global_load_ushort v183, v143, s[0:1] offset:288
	s_add_u32 s0, s0, 0x2000
	s_addc_u32 s1, s1, 0
	global_load_ushort v184, v143, s[0:1]
	global_load_ushort v185, v143, s[0:1] offset:32
	global_load_ushort v186, v143, s[0:1] offset:256
	global_load_ushort v187, v143, s[0:1] offset:288
	s_add_u32 s0, s0, 0x2000
	s_addc_u32 s1, s1, 0
	global_load_ushort v188, v143, s[0:1]
	global_load_ushort v189, v143, s[0:1] offset:32
	global_load_ushort v190, v143, s[0:1] offset:256
	global_load_ushort v191, v143, s[0:1] offset:288
	s_add_u32 s0, s0, 0x1a000
	s_addc_u32 s1, s1, 0
	s_waitcnt vmcnt(32)
; __device__ __forceinline__ unsigned cvt_pk_bf16(float lo, float hi) { const pk_f2_t v = {lo, hi}; return __builtin_bit_cast(unsigned, __builtin_convertvector(v, pk_bf2_t)); }
;     static __device__ __forceinline__ pg8::f32x4 up4(pg8::u32x2 a) { return (pg8::f32x4){__uint_as_float(a.x << 16), __uint_as_float(a.x & 0xffff0000u), __uint_as_float(a.y << 16), __uint_as_float(a.y & 0xffff0000u)}; }
;     __device__ __forceinline__ void operator()(const pg8::f32x4 (&acc)[2][2][4][2], const pg8::Unit& u, int wr, int wc, int fr, int fq) const {
;         const int row0 = u.pm * 256 + wr * 64 + fr, col0 = u.pn * 256 + wc * 32 + 4 * fq;
; #pragma unroll
;         for (int ai = 0; ai < 2; ++ai)
; #pragma unroll
;             for (int m = 0; m < 4; ++m) { const size_t r = (size_t)(row0 + ai * 128 + m * 16);
; #pragma unroll
;                 for (int bj = 0; bj < 2; ++bj)
; #pragma unroll
;                     for (int n = 0; n < 2; ++n) { const int c = col0 + bj * 128 + n * 16;
;                         const pg8::f32x4 y = up4(*(const pg8::u32x2*)(AM + r * 4096 + 2048 + c)) * acc[ai][bj][m][n];
;                         pg8::u32x2 w; w.x = pg8::cvt_pk_bf16(y[0], y[1]); w.y = pg8::cvt_pk_bf16(y[2], y[3]);
;                         *(pg8::u32x2*)(Y + r * D + c) = w; }
;                 asm volatile("" ::: "memory"); }
	v_lshlrev_b32_e32 v148, 16, v148
	v_lshlrev_b32_e32 v149, 16, v149
	v_lshlrev_b32_e32 v150, 16, v150
	v_lshlrev_b32_e32 v151, 16, v151
	v_mul_f32_e32 v64, v64, v148
	v_mul_f32_e32 v60, v60, v149
	v_mul_f32_e32 v56, v56, v150
	v_mul_f32_e32 v52, v52, v151
	v_cvt_pk_bf16_f32 v64, v64, v64
	v_cvt_pk_bf16_f32 v60, v60, v60
	v_cvt_pk_bf16_f32 v56, v56, v56
	v_cvt_pk_bf16_f32 v52, v52, v52
	global_store_short v2, v64, s[100:101]
	global_store_short v2, v60, s[100:101] offset:32
	global_store_short v2, v56, s[100:101] offset:256
	global_store_short v2, v52, s[100:101] offset:288
	s_add_u32 s100, s100, 0x1000
	s_addc_u32 s101, s101, 0
	v_lshlrev_b32_e32 v158, 16, v158
	v_lshlrev_b32_e32 v159, 16, v159
	v_lshlrev_b32_e32 v160, 16, v160
	v_lshlrev_b32_e32 v161, 16, v161
	v_mul_f32_e32 v65, v65, v158
	v_mul_f32_e32 v61, v61, v159
	v_mul_f32_e32 v57, v57, v160
	v_mul_f32_e32 v53, v53, v161
	v_cvt_pk_bf16_f32 v65, v65, v65
	v_cvt_pk_bf16_f32 v61, v61, v61
	v_cvt_pk_bf16_f32 v57, v57, v57
	v_cvt_pk_bf16_f32 v53, v53, v53
	global_store_short v2, v65, s[100:101]
	global_store_short v2, v61, s[100:101] offset:32
	global_store_short v2, v57, s[100:101] offset:256
	global_store_short v2, v53, s[100:101] offset:288
	s_add_u32 s100, s100, 0x1000
	s_addc_u32 s101, s101, 0
	v_lshlrev_b32_e32 v162, 16, v162
	v_lshlrev_b32_e32 v163, 16, v163
	v_lshlrev_b32_e32 v164, 16, v164
	v_lshlrev_b32_e32 v165, 16, v165
	v_mul_f32_e32 v66, v66, v162
	v_mul_f32_e32 v62, v62, v163
	v_mul_f32_e32 v58, v58, v164
	v_mul_f32_e32 v54, v54, v165
	v_cvt_pk_bf16_f32 v66, v66, v66
	v_cvt_pk_bf16_f32 v62, v62, v62
	v_cvt_pk_bf16_f32 v58, v58, v58
	v_cvt_pk_bf16_f32 v54, v54, v54
	global_store_short v2, v66, s[100:101]
	global_store_short v2, v62, s[100:101] offset:32
	global_store_short v2, v58, s[100:101] offset:256
	global_store_short v2, v54, s[100:101] offset:288
	s_add_u32 s100, s100, 0x1000
	s_addc_u32 s101, s101, 0
	v_lshlrev_b32_e32 v166, 16, v166
	v_lshlrev_b32_e32 v167, 16, v167
	v_lshlrev_b32_e32 v168, 16, v168
	v_lshlrev_b32_e32 v169, 16, v169
	v_mul_f32_e32 v67, v67, v166
	v_mul_f32_e32 v63, v63, v167
	v_mul_f32_e32 v59, v59, v168
	v_mul_f32_e32 v55, v55, v169
	v_cvt_pk_bf16_f32 v67, v67, v67
	v_cvt_pk_bf16_f32 v63, v63, v63
	v_cvt_pk_bf16_f32 v59, v59, v59
	v_cvt_pk_bf16_f32 v55, v55, v55
	global_store_short v2, v67, s[100:101]
	global_store_short v2, v63, s[100:101] offset:32
	global_store_short v2, v59, s[100:101] offset:256
	global_store_short v2, v55, s[100:101] offset:288
	s_add_u32 s100, s100, 0xd000
	s_addc_u32 s101, s101, 0
	global_load_ushort v148, v143, s[0:1]
	global_load_ushort v149, v143, s[0:1] offset:32
	global_load_ushort v150, v143, s[0:1] offset:256
	global_load_ushort v151, v143, s[0:1] offset:288
	s_add_u32 s0, s0, 0x2000
	s_addc_u32 s1, s1, 0
	global_load_ushort v158, v143, s[0:1]
	global_load_ushort v159, v143, s[0:1] offset:32
	global_load_ushort v160, v143, s[0:1] offset:256
	global_load_ushort v161, v143, s[0:1] offset:288
	s_add_u32 s0, s0, 0x2000
	s_addc_u32 s1, s1, 0
	global_load_ushort v162, v143, s[0:1]
	global_load_ushort v163, v143, s[0:1] offset:32
	global_load_ushort v164, v143, s[0:1] offset:256
	global_load_ushort v165, v143, s[0:1] offset:288
	s_add_u32 s0, s0, 0x2000
	s_addc_u32 s1, s1, 0
	global_load_ushort v166, v143, s[0:1]
	global_load_ushort v167, v143, s[0:1] offset:32
	global_load_ushort v168, v143, s[0:1] offset:256
	global_load_ushort v169, v143, s[0:1] offset:288
	s_add_u32 s0, s0, 0x1a000
	s_addc_u32 s1, s1, 0
	s_waitcnt vmcnt(32)
	v_lshlrev_b32_e32 v176, 16, v176
	v_lshlrev_b32_e32 v177, 16, v177
	v_lshlrev_b32_e32 v178, 16, v178
	v_lshlrev_b32_e32 v179, 16, v179
	v_mul_f32_e32 v48, v48, v176
	v_mul_f32_e32 v44, v44, v177
	v_mul_f32_e32 v40, v40, v178
	v_mul_f32_e32 v36, v36, v179
	v_cvt_pk_bf16_f32 v48, v48, v48
	v_cvt_pk_bf16_f32 v44, v44, v44
	v_cvt_pk_bf16_f32 v40, v40, v40
	v_cvt_pk_bf16_f32 v36, v36, v36
	global_store_short v2, v48, s[100:101]
	global_store_short v2, v44, s[100:101] offset:32
	global_store_short v2, v40, s[100:101] offset:256
	global_store_short v2, v36, s[100:101] offset:288
	s_add_u32 s100, s100, 0x1000
	s_addc_u32 s101, s101, 0
	v_lshlrev_b32_e32 v180, 16, v180
	v_lshlrev_b32_e32 v181, 16, v181
	v_lshlrev_b32_e32 v182, 16, v182
	v_lshlrev_b32_e32 v183, 16, v183
	v_mul_f32_e32 v49, v49, v180
	v_mul_f32_e32 v45, v45, v181
	v_mul_f32_e32 v41, v41, v182
	v_mul_f32_e32 v37, v37, v183
	v_cvt_pk_bf16_f32 v49, v49, v49
	v_cvt_pk_bf16_f32 v45, v45, v45
	v_cvt_pk_bf16_f32 v41, v41, v41
	v_cvt_pk_bf16_f32 v37, v37, v37
	global_store_short v2, v49, s[100:101]
	global_store_short v2, v45, s[100:101] offset:32
	global_store_short v2, v41, s[100:101] offset:256
	global_store_short v2, v37, s[100:101] offset:288
	s_add_u32 s100, s100, 0x1000
	s_addc_u32 s101, s101, 0
	v_lshlrev_b32_e32 v184, 16, v184
	v_lshlrev_b32_e32 v185, 16, v185
	v_lshlrev_b32_e32 v186, 16, v186
	v_lshlrev_b32_e32 v187, 16, v187
	v_mul_f32_e32 v50, v50, v184
	v_mul_f32_e32 v46, v46, v185
	v_mul_f32_e32 v42, v42, v186
	v_mul_f32_e32 v38, v38, v187
	v_cvt_pk_bf16_f32 v50, v50, v50
	v_cvt_pk_bf16_f32 v46, v46, v46
	v_cvt_pk_bf16_f32 v42, v42, v42
	v_cvt_pk_bf16_f32 v38, v38, v38
	global_store_short v2, v50, s[100:101]
	global_store_short v2, v46, s[100:101] offset:32
	global_store_short v2, v42, s[100:101] offset:256
	global_store_short v2, v38, s[100:101] offset:288
	s_add_u32 s100, s100, 0x1000
	s_addc_u32 s101, s101, 0
	v_lshlrev_b32_e32 v188, 16, v188
	v_lshlrev_b32_e32 v189, 16, v189
	v_lshlrev_b32_e32 v190, 16, v190
	v_lshlrev_b32_e32 v191, 16, v191
	v_mul_f32_e32 v51, v51, v188
	v_mul_f32_e32 v47, v47, v189
	v_mul_f32_e32 v43, v43, v190
	v_mul_f32_e32 v39, v39, v191
	v_cvt_pk_bf16_f32 v51, v51, v51
	v_cvt_pk_bf16_f32 v47, v47, v47
	v_cvt_pk_bf16_f32 v43, v43, v43
	v_cvt_pk_bf16_f32 v39, v39, v39
	global_store_short v2, v51, s[100:101]
	global_store_short v2, v47, s[100:101] offset:32
	global_store_short v2, v43, s[100:101] offset:256
	global_store_short v2, v39, s[100:101] offset:288
	s_add_u32 s100, s100, 0xd000
	s_addc_u32 s101, s101, 0
	global_load_ushort v176, v143, s[0:1]
	global_load_ushort v177, v143, s[0:1] offset:32
	global_load_ushort v178, v143, s[0:1] offset:256
	global_load_ushort v179, v143, s[0:1] offset:288
	s_add_u32 s0, s0, 0x2000
	s_addc_u32 s1, s1, 0
	global_load_ushort v180, v143, s[0:1]
	global_load_ushort v181, v143, s[0:1] offset:32
	global_load_ushort v182, v143, s[0:1] offset:256
	global_load_ushort v183, v143, s[0:1] offset:288
	s_add_u32 s0, s0, 0x2000
	s_addc_u32 s1, s1, 0
	global_load_ushort v184, v143, s[0:1]
	global_load_ushort v185, v143, s[0:1] offset:32
	global_load_ushort v186, v143, s[0:1] offset:256
	global_load_ushort v187, v143, s[0:1] offset:288
	s_add_u32 s0, s0, 0x2000
	s_addc_u32 s1, s1, 0
	global_load_ushort v188, v143, s[0:1]
	global_load_ushort v189, v143, s[0:1] offset:32
	global_load_ushort v190, v143, s[0:1] offset:256
	global_load_ushort v191, v143, s[0:1] offset:288
	s_waitcnt vmcnt(32)
; __device__ __forceinline__ unsigned cvt_pk_bf16(float lo, float hi) { const pk_f2_t v = {lo, hi}; return __builtin_bit_cast(unsigned, __builtin_convertvector(v, pk_bf2_t)); }
; #define PG8_BAR __builtin_amdgcn_s_barrier()
;     static __device__ __forceinline__ pg8::f32x4 up4(pg8::u32x2 a) { return (pg8::f32x4){__uint_as_float(a.x << 16), __uint_as_float(a.x & 0xffff0000u), __uint_as_float(a.y << 16), __uint_as_float(a.y & 0xffff0000u)}; }
; template <class Epi, class Sched, bool ALIGN_EPI = false, bool SP2 = false>
; __device__ __forceinline__ void gemm_phase(PG8_LAS unsigned char* lds, const Gemm g, const Sched& S, const Epi& E, int wave_s) {
;     ...
;         if (!has_next) break;
; #pragma unroll
;         for (int a = 0; a < 2; ++a)
; #pragma unroll
;             for (int b = 0; b < 2; ++b)
; #pragma unroll
;                 for (int m = 0; m < 4; ++m)
; #pragma unroll
;                     for (int n = 0; n < 2; ++n) acc[a][b][m][n] = (f32x4){0.f, 0.f, 0.f, 0.f};
;         cur = nxt; cA = nA; cB = nB; ++ui;
;         if constexpr (ALIGN_EPI) { if (wr == 1) PG8_BAR; }
;     __device__ __forceinline__ void operator()(const pg8::f32x4 (&acc)[2][2][4][2], const pg8::Unit& u, int wr, int wc, int fr, int fq) const {
;         const int row0 = u.pm * 256 + wr * 64 + fr, col0 = u.pn * 256 + wc * 32 + 4 * fq;
; #pragma unroll
;         for (int ai = 0; ai < 2; ++ai)
; #pragma unroll
;             for (int m = 0; m < 4; ++m) { const size_t r = (size_t)(row0 + ai * 128 + m * 16);
; #pragma unroll
;                 for (int bj = 0; bj < 2; ++bj)
; #pragma unroll
;                     for (int n = 0; n < 2; ++n) { const int c = col0 + bj * 128 + n * 16;
;                         const pg8::f32x4 y = up4(*(const pg8::u32x2*)(AM + r * 4096 + 2048 + c)) * acc[ai][bj][m][n];
;                         pg8::u32x2 w; w.x = pg8::cvt_pk_bf16(y[0], y[1]); w.y = pg8::cvt_pk_bf16(y[2], y[3]);
;                         *(pg8::u32x2*)(Y + r * D + c) = w; }
;                 asm volatile("" ::: "memory"); }
	v_lshlrev_b32_e32 v148, 16, v148
	v_lshlrev_b32_e32 v149, 16, v149
	v_lshlrev_b32_e32 v150, 16, v150
	v_lshlrev_b32_e32 v151, 16, v151
	v_mul_f32_e32 v32, v32, v148
	v_mul_f32_e32 v28, v28, v149
	v_mul_f32_e32 v24, v24, v150
	v_mul_f32_e32 v20, v20, v151
	v_cvt_pk_bf16_f32 v32, v32, v32
	v_cvt_pk_bf16_f32 v28, v28, v28
	v_cvt_pk_bf16_f32 v24, v24, v24
	v_cvt_pk_bf16_f32 v20, v20, v20
	global_store_short v2, v32, s[100:101]
	global_store_short v2, v28, s[100:101] offset:32
	global_store_short v2, v24, s[100:101] offset:256
	global_store_short v2, v20, s[100:101] offset:288
	s_add_u32 s100, s100, 0x1000
	s_addc_u32 s101, s101, 0
	v_lshlrev_b32_e32 v158, 16, v158
	v_lshlrev_b32_e32 v159, 16, v159
	v_lshlrev_b32_e32 v160, 16, v160
	v_lshlrev_b32_e32 v161, 16, v161
	v_mul_f32_e32 v33, v33, v158
	v_mul_f32_e32 v29, v29, v159
	v_mul_f32_e32 v25, v25, v160
	v_mul_f32_e32 v21, v21, v161
	v_cvt_pk_bf16_f32 v33, v33, v33
	v_cvt_pk_bf16_f32 v29, v29, v29
	v_cvt_pk_bf16_f32 v25, v25, v25
	v_cvt_pk_bf16_f32 v21, v21, v21
	global_store_short v2, v33, s[100:101]
	global_store_short v2, v29, s[100:101] offset:32
	global_store_short v2, v25, s[100:101] offset:256
	global_store_short v2, v21, s[100:101] offset:288
	s_add_u32 s100, s100, 0x1000
	s_addc_u32 s101, s101, 0
	v_lshlrev_b32_e32 v162, 16, v162
	v_lshlrev_b32_e32 v163, 16, v163
	v_lshlrev_b32_e32 v164, 16, v164
	v_lshlrev_b32_e32 v165, 16, v165
	v_mul_f32_e32 v34, v34, v162
	v_mul_f32_e32 v30, v30, v163
	v_mul_f32_e32 v26, v26, v164
	v_mul_f32_e32 v22, v22, v165
	v_cvt_pk_bf16_f32 v34, v34, v34
	v_cvt_pk_bf16_f32 v30, v30, v30
	v_cvt_pk_bf16_f32 v26, v26, v26
	v_cvt_pk_bf16_f32 v22, v22, v22
	global_store_short v2, v34, s[100:101]
	global_store_short v2, v30, s[100:101] offset:32
	global_store_short v2, v26, s[100:101] offset:256
	global_store_short v2, v22, s[100:101] offset:288
	s_add_u32 s100, s100, 0x1000
	s_addc_u32 s101, s101, 0
	v_lshlrev_b32_e32 v166, 16, v166
	v_lshlrev_b32_e32 v167, 16, v167
	v_lshlrev_b32_e32 v168, 16, v168
	v_lshlrev_b32_e32 v169, 16, v169
	v_mul_f32_e32 v35, v35, v166
	v_mul_f32_e32 v31, v31, v167
	v_mul_f32_e32 v27, v27, v168
	v_mul_f32_e32 v23, v23, v169
	v_cvt_pk_bf16_f32 v35, v35, v35
	v_cvt_pk_bf16_f32 v31, v31, v31
	v_cvt_pk_bf16_f32 v27, v27, v27
	v_cvt_pk_bf16_f32 v23, v23, v23
	global_store_short v2, v35, s[100:101]
	global_store_short v2, v31, s[100:101] offset:32
	global_store_short v2, v27, s[100:101] offset:256
	global_store_short v2, v23, s[100:101] offset:288
	s_add_u32 s100, s100, 0xd000
	s_addc_u32 s101, s101, 0
	s_waitcnt vmcnt(16)
	v_lshlrev_b32_e32 v176, 16, v176
	v_lshlrev_b32_e32 v177, 16, v177
	v_lshlrev_b32_e32 v178, 16, v178
	v_lshlrev_b32_e32 v179, 16, v179
	v_mul_f32_e32 v16, v16, v176
	v_mul_f32_e32 v12, v12, v177
	v_mul_f32_e32 v8, v8, v178
	v_mul_f32_e32 v4, v4, v179
	v_cvt_pk_bf16_f32 v16, v16, v16
	v_cvt_pk_bf16_f32 v12, v12, v12
	v_cvt_pk_bf16_f32 v8, v8, v8
	v_cvt_pk_bf16_f32 v4, v4, v4
	global_store_short v2, v16, s[100:101]
	global_store_short v2, v12, s[100:101] offset:32
	global_store_short v2, v8, s[100:101] offset:256
	global_store_short v2, v4, s[100:101] offset:288
	s_add_u32 s100, s100, 0x1000
	s_addc_u32 s101, s101, 0
	v_lshlrev_b32_e32 v180, 16, v180
	v_lshlrev_b32_e32 v181, 16, v181
	v_lshlrev_b32_e32 v182, 16, v182
	v_lshlrev_b32_e32 v183, 16, v183
	v_mul_f32_e32 v17, v17, v180
	v_mul_f32_e32 v13, v13, v181
	v_mul_f32_e32 v9, v9, v182
	v_mul_f32_e32 v5, v5, v183
	v_cvt_pk_bf16_f32 v17, v17, v17
	v_cvt_pk_bf16_f32 v13, v13, v13
	v_cvt_pk_bf16_f32 v9, v9, v9
	v_cvt_pk_bf16_f32 v5, v5, v5
	global_store_short v2, v17, s[100:101]
	global_store_short v2, v13, s[100:101] offset:32
	global_store_short v2, v9, s[100:101] offset:256
	global_store_short v2, v5, s[100:101] offset:288
	s_add_u32 s100, s100, 0x1000
	s_addc_u32 s101, s101, 0
	v_lshlrev_b32_e32 v184, 16, v184
	v_lshlrev_b32_e32 v185, 16, v185
	v_lshlrev_b32_e32 v186, 16, v186
	v_lshlrev_b32_e32 v187, 16, v187
	v_mul_f32_e32 v18, v18, v184
	v_mul_f32_e32 v14, v14, v185
	v_mul_f32_e32 v10, v10, v186
	v_mul_f32_e32 v6, v6, v187
	v_cvt_pk_bf16_f32 v18, v18, v18
	v_cvt_pk_bf16_f32 v14, v14, v14
	v_cvt_pk_bf16_f32 v10, v10, v10
	v_cvt_pk_bf16_f32 v6, v6, v6
	global_store_short v2, v18, s[100:101]
	global_store_short v2, v14, s[100:101] offset:32
	global_store_short v2, v10, s[100:101] offset:256
	global_store_short v2, v6, s[100:101] offset:288
	s_add_u32 s100, s100, 0x1000
	s_addc_u32 s101, s101, 0
	v_lshlrev_b32_e32 v188, 16, v188
	v_lshlrev_b32_e32 v189, 16, v189
	v_lshlrev_b32_e32 v190, 16, v190
	v_lshlrev_b32_e32 v191, 16, v191
	v_mul_f32_e32 v19, v19, v188
	v_mul_f32_e32 v15, v15, v189
	v_mul_f32_e32 v11, v11, v190
	v_mul_f32_e32 v7, v7, v191
	v_cvt_pk_bf16_f32 v19, v19, v19
	v_cvt_pk_bf16_f32 v15, v15, v15
	v_cvt_pk_bf16_f32 v11, v11, v11
	v_cvt_pk_bf16_f32 v7, v7, v7
	global_store_short v2, v19, s[100:101]
	global_store_short v2, v15, s[100:101] offset:32
	global_store_short v2, v11, s[100:101] offset:256
	global_store_short v2, v7, s[100:101] offset:288
	s_andn2_b64 vcc, exec, s[40:41]
	s_mov_b64 s[0:1], -1
	s_cbranch_vccnz .LBB0_1593
	s_andn2_b64 vcc, exec, s[8:9]
	s_cbranch_vccnz .LBB0_1592
	s_barrier
	s_branch .LBB0_1592
